# v113 + split-K mini GEMM pieces (sample rows of out-proj / FFN-out): fragment loads issued 8 k-steps deep into free VGPRs instead of hipcc's one-round-trip-per-MFMA-group serialisation; MFMA order unc
# baseline (speedup 1.0000x reference)
; #define LAS __attribute__((address_space(3)))
; __device__ __forceinline__ int fresh_tid() { int t = threadIdx.x; asm volatile("" : "+v"(t)); return t; }
; template <int K>
; __device__ __forceinline__ void piece(LAS unsigned char* lds, int p, const bf16* A  , const bf16* Bt, bf16* xb  , float* rowsq  ) {
;     const int tid = fresh_tid(), wid = __builtin_amdgcn_readfirstlane(tid >> 6), lane = tid & 63, r = lane & 31, hh = lane >> 5;
;     const int r0 = (p >> 4) * 64, c0 = (p & 15) * 64;
;     constexpr int KW = K / 8, NS = KW / 16;
;     static_assert(KW % 16 == 0, "K / 8 must be a multiple of 16");
;     const bf16* ap = A + (size_t)(r0 + r) * K + wid * KW + 8 * hh; const bf16* bp = Bt + (size_t)(c0 + r) * K + wid * KW + 8 * hh;
;     f32x16 acc[2][2] = {};
;     constexpr int U = (NS % 11 == 0) ? 11 : 8;
;     static_assert(NS % U == 0, "batching");
;     for (int kb = 0; kb < NS; kb += U) {
;         bf16x8 a0[U], a1[U], b0[U], b1[U];
; #pragma unroll
;         for (int u = 0; u < U; ++u) { a0[u] = *(const bf16x8*)(ap + (kb + u) * 16); a1[u] = *(const bf16x8*)(ap + (size_t)32 * K + (kb + u) * 16);
;                                       b0[u] = *(const bf16x8*)(bp + (kb + u) * 16); b1[u] = *(const bf16x8*)(bp + (size_t)32 * K + (kb + u) * 16); }
; #pragma unroll
;         for (int u = 0; u < U; ++u) {
;             acc[0][0] = __builtin_amdgcn_mfma_f32_32x32x16_bf16(a0[u], b0[u], acc[0][0], 0, 0, 0); acc[0][1] = __builtin_amdgcn_mfma_f32_32x32x16_bf16(a0[u], b1[u], acc[0][1], 0, 0, 0);
;             acc[1][0] = __builtin_amdgcn_mfma_f32_32x32x16_bf16(a1[u], b0[u], acc[1][0], 0, 0, 0); acc[1][1] = __builtin_amdgcn_mfma_f32_32x32x16_bf16(a1[u], b1[u], acc[1][1], 0, 0, 0); }
.LBB0_857:
	v_mov_b32_e32 v3, 0x20258
	v_mov_b32_e32 v5, 0x20258
	v_add_u32_e32 v3, 0, v3
	ds_read_b32 v4, v3
	ds_read_b32 v3, v3 offset:4
	v_mov_b32_e32 v69, v0
	s_mov_b32 s15, 0x15d00000
	s_waitcnt lgkmcnt(1)
	v_readfirstlane_b32 s16, v4
	s_waitcnt lgkmcnt(0)
	v_readfirstlane_b32 s17, v3
	v_add_u32_e32 v3, 0, v5
	ds_read_b32 v4, v3
	ds_read_b32 v3, v3 offset:4
	v_mov_b32_e32 v5, 0x20258
	s_waitcnt lgkmcnt(1)
	v_readfirstlane_b32 s0, v4
	v_add_u32_e32 v5, 0, v5
	ds_read_b32 v6, v5
	v_mov_b32_e32 v4, 0x20258
	s_waitcnt lgkmcnt(1)
	v_readfirstlane_b32 s1, v3
	ds_read_b32 v3, v5 offset:4
	s_add_u32 s18, s0, s43
	v_add_u32_e32 v4, 0, v4
	ds_read_b32 v5, v4
	ds_read_b32 v4, v4 offset:4
	s_addc_u32 s19, s1, s42
	s_waitcnt lgkmcnt(3)
	v_readfirstlane_b32 s0, v6
	s_waitcnt lgkmcnt(2)
	v_readfirstlane_b32 s1, v3
	s_add_u32 s0, s0, 0xcc00000
	s_addc_u32 s1, s1, 0
	s_waitcnt lgkmcnt(1)
	v_readfirstlane_b32 s8, v5
	s_waitcnt lgkmcnt(0)
	v_readfirstlane_b32 s9, v4
	s_add_u32 s12, s8, s6
	s_addc_u32 s13, s9, s7
	v_readfirstlane_b32 s8, v69
	s_ashr_i32 s9, s8, 6
	v_and_b32_e32 v3, 31, v69
	s_and_b32 s8, s10, 0xffffffc0
	v_or_b32_e32 v4, s8, v3
	v_ashrrev_i32_e32 v5, 31, v4
	v_lshlrev_b64 v[4:5], 11, v[4:5]
	v_lshl_add_u64 v[4:5], s[16:17], 0, v[4:5]
	s_lshl_b32 s16, s9, 7
	s_ashr_i32 s17, s16, 31
	s_and_b32 s14, s11, 15
	s_lshl_b64 s[16:17], s[16:17], 1
	v_lshrrev_b32_e32 v6, 1, v69
	v_lshl_add_u64 v[4:5], v[4:5], 0, s[16:17]
	v_and_b32_e32 v196, 16, v6
	v_lshl_or_b32 v68, s14, 6, v3
	s_waitcnt vmcnt(8)
	v_lshl_add_u64 v[44:45], v[4:5], 0, v[196:197]
	v_lshlrev_b32_e32 v4, 11, v68
	v_mov_b32_e32 v5, v197
	v_lshl_add_u64 v[4:5], s[18:19], 0, v[4:5]
	v_lshl_add_u64 v[4:5], v[4:5], 0, s[16:17]
	s_waitcnt vmcnt(7)
	v_lshl_add_u64 v[46:47], v[4:5], 0, v[196:197]
	v_add_co_u32_e32 v4, vcc, s15, v44
	s_mov_b64 s[16:17], 0x15d00000
	s_nop 0
	v_addc_co_u32_e32 v5, vcc, 0, v45, vcc
	s_mov_b32 s15, 0x880000
	v_lshl_add_u64 v[86:87], v[44:45], 0, s[16:17]
	v_add_co_u32_e32 v4, vcc, s15, v46
	s_mov_b32 s15, 0x890000
	s_nop 0
	v_addc_co_u32_e32 v5, vcc, 0, v47, vcc
	v_add_co_u32_e32 v90, vcc, s15, v46
	s_nop 0
	v_addc_co_u32_e32 v91, vcc, 0, v47, vcc
	s_mov_b64 s[16:17], 0x880000
	v_lshl_add_u64 v[92:93], v[46:47], 0, s[16:17]
	s_mov_b32 s15, 0x15d10000
	v_add_co_u32_e32 v94, vcc, s15, v44
	s_lshl_b32 s9, s9, 14
	s_nop 0
	v_addc_co_u32_e32 v95, vcc, 0, v45, vcc
	s_add_i32 s9, s9, 0
	global_load_dwordx4 v[98:101], v[86:87], off
	global_load_dwordx4 v[106:109], v[92:93], off
	global_load_dwordx4 v[110:113], v[90:91], off
	global_load_dwordx4 v[102:105], v[94:95], off
	global_load_dwordx4 v[114:117], v[86:87], off offset:32
	global_load_dwordx4 v[122:125], v[92:93], off offset:32
	global_load_dwordx4 v[126:129], v[90:91], off offset:32
	global_load_dwordx4 v[118:121], v[94:95], off offset:32
	global_load_dwordx4 v[130:133], v[86:87], off offset:64
	global_load_dwordx4 v[138:141], v[92:93], off offset:64
	global_load_dwordx4 v[142:145], v[90:91], off offset:64
	global_load_dwordx4 v[134:137], v[94:95], off offset:64
	global_load_dwordx4 v[146:149], v[86:87], off offset:96
	global_load_dwordx4 v[154:157], v[92:93], off offset:96
	global_load_dwordx4 v[158:161], v[90:91], off offset:96
	global_load_dwordx4 v[150:153], v[94:95], off offset:96
	global_load_dwordx4 v[162:165], v[86:87], off offset:128
	global_load_dwordx4 v[170:173], v[92:93], off offset:128
	global_load_dwordx4 v[174:177], v[90:91], off offset:128
	global_load_dwordx4 v[166:169], v[94:95], off offset:128
	global_load_dwordx4 v[178:181], v[86:87], off offset:160
	global_load_dwordx4 v[186:189], v[92:93], off offset:160
	global_load_dwordx4 v[190:193], v[90:91], off offset:160
	global_load_dwordx4 v[182:185], v[94:95], off offset:160
	global_load_dwordx4 v[210:213], v[86:87], off offset:192
	global_load_dwordx4 v[218:221], v[92:93], off offset:192
	global_load_dwordx4 v[222:225], v[90:91], off offset:192
	global_load_dwordx4 v[214:217], v[94:95], off offset:192
	global_load_dwordx4 v[70:73], v[86:87], off offset:224
	global_load_dwordx4 v[78:81], v[92:93], off offset:224
	global_load_dwordx4 v[82:85], v[90:91], off offset:224
	global_load_dwordx4 v[74:77], v[94:95], off offset:224
	s_waitcnt vmcnt(30)
	v_mfma_f32_32x32x16_bf16 v[4:19], v[98:101], v[106:109], 0
	s_waitcnt vmcnt(29)
	v_mfma_f32_32x32x16_bf16 v[52:67], v[98:101], v[110:113], 0
	s_waitcnt vmcnt(28)
	v_mfma_f32_32x32x16_bf16 v[20:35], v[102:105], v[106:109], 0
	v_mfma_f32_32x32x16_bf16 v[36:51], v[102:105], v[110:113], 0
	s_waitcnt vmcnt(26)
	v_mfma_f32_32x32x16_bf16 v[4:19], v[114:117], v[122:125], v[4:19]
	s_waitcnt vmcnt(25)
	v_mfma_f32_32x32x16_bf16 v[52:67], v[114:117], v[126:129], v[52:67]
	s_waitcnt vmcnt(24)
	v_mfma_f32_32x32x16_bf16 v[20:35], v[118:121], v[122:125], v[20:35]
	v_mfma_f32_32x32x16_bf16 v[36:51], v[118:121], v[126:129], v[36:51]
	s_waitcnt vmcnt(22)
	v_mfma_f32_32x32x16_bf16 v[4:19], v[130:133], v[138:141], v[4:19]
	s_waitcnt vmcnt(21)
	v_mfma_f32_32x32x16_bf16 v[52:67], v[130:133], v[142:145], v[52:67]
	s_waitcnt vmcnt(20)
	v_mfma_f32_32x32x16_bf16 v[20:35], v[134:137], v[138:141], v[20:35]
	v_mfma_f32_32x32x16_bf16 v[36:51], v[134:137], v[142:145], v[36:51]
	s_waitcnt vmcnt(18)
	v_mfma_f32_32x32x16_bf16 v[4:19], v[146:149], v[154:157], v[4:19]
	s_waitcnt vmcnt(17)
	v_mfma_f32_32x32x16_bf16 v[52:67], v[146:149], v[158:161], v[52:67]
	s_waitcnt vmcnt(16)
	v_mfma_f32_32x32x16_bf16 v[20:35], v[150:153], v[154:157], v[20:35]
	v_mfma_f32_32x32x16_bf16 v[36:51], v[150:153], v[158:161], v[36:51]
	s_waitcnt vmcnt(14)
	v_mfma_f32_32x32x16_bf16 v[4:19], v[162:165], v[170:173], v[4:19]
	s_waitcnt vmcnt(13)
; #define LAS __attribute__((address_space(3)))
; template <int K>
; __device__ __forceinline__ void piece(LAS unsigned char* lds, int p, const bf16* A  , const bf16* Bt, bf16* xb  , float* rowsq  ) {
;     ...
;         for (int u = 0; u < U; ++u) {
;             acc[0][0] = __builtin_amdgcn_mfma_f32_32x32x16_bf16(a0[u], b0[u], acc[0][0], 0, 0, 0); acc[0][1] = __builtin_amdgcn_mfma_f32_32x32x16_bf16(a0[u], b1[u], acc[0][1], 0, 0, 0);
;             acc[1][0] = __builtin_amdgcn_mfma_f32_32x32x16_bf16(a1[u], b0[u], acc[1][0], 0, 0, 0); acc[1][1] = __builtin_amdgcn_mfma_f32_32x32x16_bf16(a1[u], b1[u], acc[1][1], 0, 0, 0); }
;     }
;     LAS float* P = (LAS float*)lds;
; #pragma unroll
;     for (int i = 0; i < 2; ++i)
; #pragma unroll
;         for (int j = 0; j < 2; ++j)
; #pragma unroll
;             for (int q = 0; q < 16; ++q) P[(((wid * 2 + i) * 2 + j) * 16 + q) * 64 + lane] = acc[i][j][q];
;     __syncthreads();
	v_mfma_f32_32x32x16_bf16 v[52:67], v[162:165], v[174:177], v[52:67]
	s_waitcnt vmcnt(12)
	v_mfma_f32_32x32x16_bf16 v[20:35], v[166:169], v[170:173], v[20:35]
	v_mfma_f32_32x32x16_bf16 v[36:51], v[166:169], v[174:177], v[36:51]
	s_waitcnt vmcnt(10)
	v_mfma_f32_32x32x16_bf16 v[4:19], v[178:181], v[186:189], v[4:19]
	s_waitcnt vmcnt(9)
	v_mfma_f32_32x32x16_bf16 v[52:67], v[178:181], v[190:193], v[52:67]
	s_waitcnt vmcnt(8)
	v_mfma_f32_32x32x16_bf16 v[20:35], v[182:185], v[186:189], v[20:35]
	v_mfma_f32_32x32x16_bf16 v[36:51], v[182:185], v[190:193], v[36:51]
	s_waitcnt vmcnt(6)
	v_mfma_f32_32x32x16_bf16 v[4:19], v[210:213], v[218:221], v[4:19]
	s_waitcnt vmcnt(5)
	v_mfma_f32_32x32x16_bf16 v[52:67], v[210:213], v[222:225], v[52:67]
	s_waitcnt vmcnt(4)
	v_mfma_f32_32x32x16_bf16 v[20:35], v[214:217], v[218:221], v[20:35]
	v_mfma_f32_32x32x16_bf16 v[36:51], v[214:217], v[222:225], v[36:51]
	s_waitcnt vmcnt(2)
	v_mfma_f32_32x32x16_bf16 v[4:19], v[70:73], v[78:81], v[4:19]
	s_waitcnt vmcnt(1)
	v_mfma_f32_32x32x16_bf16 v[52:67], v[70:73], v[82:85], v[52:67]
	s_waitcnt vmcnt(0)
	v_mfma_f32_32x32x16_bf16 v[20:35], v[74:77], v[78:81], v[20:35]
	v_mfma_f32_32x32x16_bf16 v[36:51], v[74:77], v[82:85], v[36:51]
	v_and_b32_e32 v94, 63, v69
	v_lshl_add_u32 v94, v94, 2, s9
	s_nop 11
	ds_write2st64_b32 v94, v4, v5 offset1:1
	ds_write2st64_b32 v94, v6, v7 offset0:2 offset1:3
	ds_write2st64_b32 v94, v8, v9 offset0:4 offset1:5
	v_lshrrev_b32_e32 v4, 3, v69
	ds_write2st64_b32 v94, v10, v11 offset0:6 offset1:7
	ds_write2st64_b32 v94, v12, v13 offset0:8 offset1:9
	ds_write2st64_b32 v94, v14, v15 offset0:10 offset1:11
	ds_write2st64_b32 v94, v16, v17 offset0:12 offset1:13
	ds_write2st64_b32 v94, v18, v19 offset0:14 offset1:15
	s_nop 5
	ds_write2st64_b32 v94, v52, v53 offset0:16 offset1:17
	ds_write2st64_b32 v94, v54, v55 offset0:18 offset1:19
	v_lshrrev_b32_e32 v8, 5, v69
	v_bfe_u32 v5, v69, 6, 2
	v_and_b32_e32 v6, 24, v8
	v_mov_b32_e32 v13, v197
	ds_write2st64_b32 v94, v56, v57 offset0:20 offset1:21
	ds_write2st64_b32 v94, v58, v59 offset0:22 offset1:23
	ds_write2st64_b32 v94, v60, v61 offset0:24 offset1:25
	ds_write2st64_b32 v94, v62, v63 offset0:26 offset1:27
	ds_write2st64_b32 v94, v64, v65 offset0:28 offset1:29
	ds_write2st64_b32 v94, v66, v67 offset0:30 offset1:31
	s_nop 5
	ds_write2st64_b32 v94, v20, v21 offset0:32 offset1:33
	ds_write2st64_b32 v94, v22, v23 offset0:34 offset1:35
	ds_write2st64_b32 v94, v24, v25 offset0:36 offset1:37
	ds_write2st64_b32 v94, v26, v27 offset0:38 offset1:39
	ds_write2st64_b32 v94, v28, v29 offset0:40 offset1:41
	ds_write2st64_b32 v94, v30, v31 offset0:42 offset1:43
	ds_write2st64_b32 v94, v32, v33 offset0:44 offset1:45
	ds_write2st64_b32 v94, v34, v35 offset0:46 offset1:47
	s_nop 11
	ds_write2st64_b32 v94, v36, v37 offset0:48 offset1:49
	ds_write2st64_b32 v94, v38, v39 offset0:50 offset1:51
	ds_write2st64_b32 v94, v40, v41 offset0:52 offset1:53
	ds_write2st64_b32 v94, v42, v43 offset0:54 offset1:55
	ds_write2st64_b32 v94, v44, v45 offset0:56 offset1:57
	ds_write2st64_b32 v94, v46, v47 offset0:58 offset1:59
	ds_write2st64_b32 v94, v48, v49 offset0:60 offset1:61
	ds_write2st64_b32 v94, v50, v51 offset0:62 offset1:63
	v_and_or_b32 v40, v4, 4, s8
	v_ashrrev_i32_e32 v4, 6, v69
	v_and_b32_e32 v4, 0xffffffe0, v4
	v_add_u32_e32 v4, v40, v4
	s_lshl_b32 s8, s14, 7
	v_or3_b32 v6, v4, v5, v6
	s_add_u32 s8, s0, s8
	v_ashrrev_i32_e32 v7, 31, v6
	s_addc_u32 s9, s1, 0
	v_and_b32_e32 v48, 32, v8
	v_lshlrev_b64 v[24:25], 11, v[6:7]
	v_lshl_add_u64 v[4:5], s[8:9], 0, v[24:25]
	v_lshlrev_b32_e32 v196, 1, v48
	v_lshl_add_u64 v[4:5], v[4:5], 0, v[196:197]
	v_lshlrev_b32_e32 v26, 1, v3
	v_mov_b32_e32 v27, v197
	v_lshl_add_u64 v[8:9], v[4:5], 0, v[26:27]
	v_add_u32_e32 v4, 0x200, v69
	v_ashrrev_i32_e32 v5, 6, v4
	v_and_b32_e32 v5, 0xffffffe0, v5
	v_lshrrev_b32_e32 v11, 5, v4
	v_bfe_u32 v10, v4, 6, 2
	v_and_b32_e32 v4, 24, v11
	v_add_u32_e32 v5, v40, v5
	v_or3_b32 v4, v5, v10, v4
	v_ashrrev_i32_e32 v5, 31, v4
	v_and_b32_e32 v49, 32, v11
	v_lshlrev_b64 v[28:29], 11, v[4:5]
	v_lshl_add_u64 v[10:11], s[8:9], 0, v[28:29]
	v_lshlrev_b32_e32 v12, 1, v49
	v_lshl_add_u64 v[10:11], v[10:11], 0, v[12:13]
	s_waitcnt lgkmcnt(0)
	s_barrier
	v_lshl_add_u64 v[10:11], v[10:11], 0, v[26:27]
	global_load_ushort v50, v[8:9], off
	global_load_ushort v51, v[10:11], off
	v_add_u32_e32 v8, 0x400, v69
	v_ashrrev_i32_e32 v9, 6, v8
	v_and_b32_e32 v9, 0xffffffe0, v9
	v_lshrrev_b32_e32 v11, 5, v8
	v_bfe_u32 v10, v8, 6, 2
	v_and_b32_e32 v8, 24, v11
	v_add_u32_e32 v9, v40, v9
	v_or3_b32 v8, v9, v10, v8
	v_ashrrev_i32_e32 v9, 31, v8
	v_and_b32_e32 v52, 32, v11
	v_lshlrev_b64 v[20:21], 11, v[8:9]
	v_lshl_add_u64 v[8:9], s[8:9], 0, v[20:21]
	v_lshlrev_b32_e32 v10, 1, v52
	v_mov_b32_e32 v11, v197
	v_lshl_add_u64 v[8:9], v[8:9], 0, v[10:11]
	v_lshl_add_u64 v[30:31], v[8:9], 0, v[26:27]
	v_add_u32_e32 v8, 0x600, v69
	v_ashrrev_i32_e32 v9, 6, v8
	v_and_b32_e32 v9, 0xffffffe0, v9
	v_lshrrev_b32_e32 v11, 5, v8
	v_bfe_u32 v10, v8, 6, 2
	v_and_b32_e32 v8, 24, v11
	v_add_u32_e32 v9, v40, v9
	v_or3_b32 v8, v9, v10, v8
	v_ashrrev_i32_e32 v9, 31, v8
	v_and_b32_e32 v53, 32, v11
	v_lshlrev_b64 v[22:23], 11, v[8:9]
	v_lshl_add_u64 v[8:9], s[8:9], 0, v[22:23]
	v_lshlrev_b32_e32 v10, 1, v53
	v_mov_b32_e32 v11, v197
	v_lshl_add_u64 v[8:9], v[8:9], 0, v[10:11]
	v_lshl_add_u64 v[32:33], v[8:9], 0, v[26:27]
	v_add_u32_e32 v8, 0x800, v69
	v_ashrrev_i32_e32 v9, 6, v8
	v_and_b32_e32 v9, 0xffffffe0, v9
	v_bfe_u32 v10, v8, 6, 2
	v_lshrrev_b32_e32 v8, 5, v8
	v_and_b32_e32 v8, 24, v8
	v_add_u32_e32 v9, v40, v9
	v_or3_b32 v10, v9, v10, v8
	v_ashrrev_i32_e32 v11, 31, v10
	v_lshlrev_b64 v[16:17], 11, v[10:11]
; __device__ __forceinline__ unsigned f2bf(float f) { unsigned u = __builtin_bit_cast(unsigned, f); return (u + 0x7fffu + ((u >> 16) & 1u)) >> 16; }
; __device__ __forceinline__ int crow(int r, int hi) { return (r & 3) + 8 * (r >> 2) + 4 * hi; }
; __device__ __forceinline__ int crow(int r, int hi) { return (r & 3) + 8 * (r >> 2) + 4 * hi; }
; __device__ __forceinline__ int crow(int r, int hi) { return (r & 3) + 8 * (r >> 2) + 4 * hi; }
; template <int K>
; __device__ __forceinline__ void piece(LAS unsigned char* lds, int p, const bf16* A  , const bf16* Bt, bf16* xb  , float* rowsq  ) {
;     ...
;     float vv[8]; unsigned short xin[8];
; #pragma unroll
;     for (int q = 0; q < 8; ++q) { const int e = tid + 512 * q; const int ln = e & 63, reg = (e >> 6) & 15, j = (e >> 10) & 1, i = e >> 11;
;         xin[q] = xb[(size_t)(r0 + 32 * i + crow(reg, ln >> 5)) * 1024 + c0 + 32 * j + (ln & 31)]; }
; #pragma unroll
;     for (int q = 0; q < 8; ++q) { const int e = tid + 512 * q;
;         float s = 0.f;
; #pragma unroll
;         for (int w = 0; w < 8; ++w) s += P[w * 4096 + e];
;         const int ln = e & 63, reg = (e >> 6) & 15, j = (e >> 10) & 1, i = e >> 11;
;         const int row = r0 + 32 * i + crow(reg, ln >> 5), col = c0 + 32 * j + (ln & 31);
;         const float v = bf2f(xin[q]) + s;
;         xb[(size_t)row * 1024 + col] = (bf16)f2bf(v); vv[q] = v; }
	v_lshl_add_u64 v[8:9], s[8:9], 0, v[16:17]
	v_lshl_add_u64 v[8:9], v[8:9], 0, v[196:197]
	v_lshl_add_u64 v[34:35], v[8:9], 0, v[26:27]
	v_add_u32_e32 v8, 0xa00, v69
	v_ashrrev_i32_e32 v9, 6, v8
	v_and_b32_e32 v9, 0xffffffe0, v9
	v_lshrrev_b32_e32 v13, 5, v8
	v_bfe_u32 v12, v8, 6, 2
	v_and_b32_e32 v8, 24, v13
	v_add_u32_e32 v9, v40, v9
	v_or3_b32 v8, v9, v12, v8
	v_ashrrev_i32_e32 v9, 31, v8
	v_and_b32_e32 v54, 32, v13
	v_lshlrev_b64 v[18:19], 11, v[8:9]
	v_lshl_add_u64 v[12:13], s[8:9], 0, v[18:19]
	v_lshlrev_b32_e32 v196, 1, v54
	v_lshl_add_u64 v[12:13], v[12:13], 0, v[196:197]
	v_lshl_add_u64 v[36:37], v[12:13], 0, v[26:27]
	v_add_u32_e32 v12, 0xc00, v69
	v_ashrrev_i32_e32 v13, 6, v12
	v_and_b32_e32 v13, 0xffffffe0, v13
	v_lshrrev_b32_e32 v15, 5, v12
	v_bfe_u32 v14, v12, 6, 2
	v_and_b32_e32 v12, 24, v15
	v_add_u32_e32 v13, v40, v13
	v_or3_b32 v12, v13, v14, v12
	v_ashrrev_i32_e32 v13, 31, v12
	v_and_b32_e32 v55, 32, v15
	v_lshlrev_b64 v[14:15], 11, v[12:13]
	v_lshl_add_u64 v[12:13], s[8:9], 0, v[14:15]
	v_lshlrev_b32_e32 v196, 1, v55
	v_lshl_add_u64 v[12:13], v[12:13], 0, v[196:197]
	v_lshl_add_u64 v[38:39], v[12:13], 0, v[26:27]
	v_add_u32_e32 v12, 0xe00, v69
	v_ashrrev_i32_e32 v13, 6, v12
	v_and_b32_e32 v13, 0xffffffe0, v13
	v_lshrrev_b32_e32 v42, 5, v12
	v_bfe_u32 v41, v12, 6, 2
	v_and_b32_e32 v12, 24, v42
	v_add_u32_e32 v13, v40, v13
	v_or3_b32 v12, v13, v41, v12
	v_ashrrev_i32_e32 v13, 31, v12
	v_and_b32_e32 v56, 32, v42
	v_lshlrev_b64 v[12:13], 11, v[12:13]
	v_lshl_add_u64 v[40:41], s[8:9], 0, v[12:13]
	v_lshlrev_b32_e32 v196, 1, v56
	v_lshl_add_u64 v[40:41], v[40:41], 0, v[196:197]
	v_lshl_add_u32 v57, v69, 2, 0
	v_lshl_add_u64 v[26:27], v[40:41], 0, v[26:27]
	ds_read2st64_b32 v[40:41], v57 offset1:8
	ds_read2st64_b32 v[42:43], v57 offset0:64 offset1:72
	ds_read2st64_b32 v[44:45], v57 offset0:128 offset1:136
	ds_read2st64_b32 v[46:47], v57 offset0:192 offset1:200
	global_load_ushort v58, v[30:31], off
	global_load_ushort v59, v[32:33], off
	global_load_ushort v60, v[34:35], off
	s_nop 0
	global_load_ushort v36, v[36:37], off
	s_nop 0
	global_load_ushort v37, v[38:39], off
	s_nop 0
	global_load_ushort v38, v[26:27], off
	s_waitcnt lgkmcnt(3)
	v_add_f32_e32 v26, 0, v40
	s_waitcnt lgkmcnt(2)
	v_add_f32_e32 v26, v26, v42
	s_waitcnt lgkmcnt(1)
	v_add_f32_e32 v26, v26, v44
	s_waitcnt lgkmcnt(0)
	v_add_f32_e32 v26, v26, v46
	v_add_u32_e32 v27, 0x10000, v57
	v_add_u32_e32 v30, 0x14000, v57
	v_add_u32_e32 v31, 0x18000, v57
	v_add_u32_e32 v32, 0x1c000, v57
	v_add_u32_e32 v33, 0x10800, v57
	v_add_u32_e32 v34, 0x14800, v57
	v_add_u32_e32 v35, 0x18800, v57
	v_add_u32_e32 v39, 0x1c800, v57
	ds_read_b32 v27, v27
	ds_read_b32 v30, v30
	ds_read_b32 v31, v31
	ds_read_b32 v32, v32
	ds_read_b32 v33, v33
	ds_read_b32 v34, v34
	ds_read_b32 v35, v35
	ds_read_b32 v39, v39
	s_waitcnt lgkmcnt(7)
	v_add_f32_e32 v26, v26, v27
	s_waitcnt lgkmcnt(6)
	v_add_f32_e32 v26, v26, v30
	s_waitcnt lgkmcnt(5)
	v_add_f32_e32 v26, v26, v31
	s_waitcnt lgkmcnt(4)
	v_add_f32_e32 v26, v26, v32
	s_waitcnt vmcnt(7)
	v_lshlrev_b32_e32 v30, 16, v50
	v_or_b32_e32 v27, v68, v48
	v_add_f32_e32 v40, v26, v30
	v_bfe_u32 v26, v40, 16, 1
	v_lshl_add_u64 v[24:25], s[0:1], 0, v[24:25]
	v_lshlrev_b32_e32 v196, 1, v27
	v_add3_u32 v26, v40, v26, s51
	v_lshl_add_u64 v[24:25], v[24:25], 0, v[196:197]
	global_store_short_d16_hi v[24:25], v26, off
	v_add_f32_e32 v24, 0, v41
	v_add_f32_e32 v24, v24, v43
	v_add_f32_e32 v24, v24, v45
	v_add_f32_e32 v24, v24, v47
	s_waitcnt lgkmcnt(3)
	v_add_f32_e32 v24, v24, v33
	s_waitcnt lgkmcnt(2)
	v_add_f32_e32 v24, v24, v34
	s_waitcnt lgkmcnt(1)
	v_add_f32_e32 v24, v24, v35
	s_waitcnt lgkmcnt(0)
	v_add_f32_e32 v24, v24, v39
	s_waitcnt vmcnt(7)
	v_lshlrev_b32_e32 v26, 16, v51
	v_add_f32_e32 v24, v24, v26
	v_or_b32_e32 v25, v68, v49
	v_bfe_u32 v26, v24, 16, 1
	v_add3_u32 v39, v24, v26, s51
	v_lshl_add_u64 v[26:27], s[0:1], 0, v[28:29]
	v_lshlrev_b32_e32 v28, 1, v25
	v_mov_b32_e32 v29, v197
	v_lshl_add_u64 v[26:27], v[26:27], 0, v[28:29]
	ds_read2st64_b32 v[28:29], v57 offset0:16 offset1:24
	ds_read2st64_b32 v[30:31], v57 offset0:80 offset1:88
	ds_read2st64_b32 v[32:33], v57 offset0:144 offset1:152
	ds_read2st64_b32 v[34:35], v57 offset0:208 offset1:216
	global_store_short_d16_hi v[26:27], v39, off
	s_waitcnt lgkmcnt(3)
	v_add_f32_e32 v25, 0, v28
	s_waitcnt lgkmcnt(2)
	v_add_f32_e32 v25, v25, v30
	s_waitcnt lgkmcnt(1)
	v_add_f32_e32 v25, v25, v32
	s_waitcnt lgkmcnt(0)
	v_add_f32_e32 v25, v25, v34
	v_add_u32_e32 v26, 0x11000, v57
	v_add_u32_e32 v27, 0x15000, v57
	v_add_u32_e32 v28, 0x19000, v57
	v_add_u32_e32 v30, 0x1d000, v57
	v_add_u32_e32 v32, 0x11800, v57
	v_add_u32_e32 v34, 0x15800, v57
	v_add_u32_e32 v39, 0x19800, v57
	v_add_u32_e32 v41, 0x1d800, v57
	ds_read_b32 v26, v26
	ds_read_b32 v27, v27
	ds_read_b32 v28, v28
	ds_read_b32 v30, v30
	ds_read_b32 v32, v32
	ds_read_b32 v34, v34
	ds_read_b32 v39, v39
	ds_read_b32 v41, v41
	s_waitcnt lgkmcnt(7)
	v_add_f32_e32 v25, v25, v26
	s_waitcnt lgkmcnt(6)
	v_add_f32_e32 v25, v25, v27
	s_waitcnt lgkmcnt(5)
	v_add_f32_e32 v25, v25, v28
	s_waitcnt lgkmcnt(4)
	v_add_f32_e32 v25, v25, v30
	v_or_b32_e32 v26, v68, v52
	v_lshl_add_u64 v[20:21], s[0:1], 0, v[20:21]
	v_lshlrev_b32_e32 v26, 1, v26
	v_lshl_add_u64 v[22:23], s[0:1], 0, v[22:23]
	v_lshl_add_u64 v[16:17], s[0:1], 0, v[16:17]
	v_lshl_add_u64 v[16:17], v[16:17], 0, v[196:197]
	v_lshl_add_u64 v[18:19], s[0:1], 0, v[18:19]
	v_lshl_add_u64 v[14:15], s[0:1], 0, v[14:15]
	s_lshl_b32 s8, s14, 2
	s_waitcnt vmcnt(7)
; __device__ __forceinline__ unsigned f2bf(float f) { unsigned u = __builtin_bit_cast(unsigned, f); return (u + 0x7fffu + ((u >> 16) & 1u)) >> 16; }
; __device__ __forceinline__ int crow(int r, int hi) { return (r & 3) + 8 * (r >> 2) + 4 * hi; }
; __device__ __forceinline__ int crow(int r, int hi) { return (r & 3) + 8 * (r >> 2) + 4 * hi; }
; __device__ __forceinline__ int crow(int r, int hi) { return (r & 3) + 8 * (r >> 2) + 4 * hi; }
; template <int K>
; __device__ __forceinline__ void piece(LAS unsigned char* lds, int p, const bf16* A  , const bf16* Bt, bf16* xb  , float* rowsq  ) {
;     ...
; #pragma unroll
;     for (int q = 0; q < 8; ++q) { const int e = tid + 512 * q;
;         float s = 0.f;
; #pragma unroll
;         for (int w = 0; w < 8; ++w) s += P[w * 4096 + e];
;         const int ln = e & 63, reg = (e >> 6) & 15, j = (e >> 10) & 1, i = e >> 11;
;         const int row = r0 + 32 * i + crow(reg, ln >> 5), col = c0 + 32 * j + (ln & 31);
;         const float v = bf2f(xin[q]) + s;
;         xb[(size_t)row * 1024 + col] = (bf16)f2bf(v); vv[q] = v; }
; #pragma unroll
;     for (int q = 0; q < 8; ++q) { if (q & 2) continue;
;         float sq = vv[q] * vv[q] + vv[q + 2] * vv[q + 2]; sq += __shfl_xor(sq, 1); sq += __shfl_xor(sq, 2); sq += __shfl_xor(sq, 4); sq += __shfl_xor(sq, 8); sq += __shfl_xor(sq, 16);
;         const int e = tid + 512 * q, ln = e & 63, reg = (e >> 6) & 15, i = e >> 11; const int row = r0 + 32 * i + crow(reg, ln >> 5);
;         if ((ln & 31) == 0) rowsq[(size_t)row * 16 + (p & 15)] = sq; }
	v_lshlrev_b32_e32 v27, 16, v58
	v_add_f32_e32 v25, v25, v27
	v_bfe_u32 v27, v25, 16, 1
	v_add3_u32 v28, v25, v27, s51
	v_mov_b32_e32 v27, v197
	v_lshl_add_u64 v[20:21], v[20:21], 0, v[26:27]
	global_store_short_d16_hi v[20:21], v28, off
	v_add_f32_e32 v20, 0, v29
	v_add_f32_e32 v20, v20, v31
	v_add_f32_e32 v20, v20, v33
	v_add_f32_e32 v20, v20, v35
	s_waitcnt lgkmcnt(3)
	v_add_f32_e32 v20, v20, v32
	s_waitcnt lgkmcnt(2)
	v_add_f32_e32 v20, v20, v34
	s_waitcnt lgkmcnt(1)
	v_add_f32_e32 v20, v20, v39
	s_waitcnt lgkmcnt(0)
	v_add_f32_e32 v20, v20, v41
	s_waitcnt vmcnt(7)
	v_lshlrev_b32_e32 v26, 16, v59
	v_add_f32_e32 v20, v20, v26
	v_or_b32_e32 v21, v68, v53
	v_bfe_u32 v26, v20, 16, 1
	v_add3_u32 v34, v20, v26, s51
	v_lshlrev_b32_e32 v26, 1, v21
	v_lshl_add_u64 v[22:23], v[22:23], 0, v[26:27]
	ds_read2st64_b32 v[26:27], v57 offset0:32 offset1:40
	ds_read2st64_b32 v[28:29], v57 offset0:96 offset1:104
	ds_read2st64_b32 v[30:31], v57 offset0:160 offset1:168
	ds_read2st64_b32 v[32:33], v57 offset0:224 offset1:232
	global_store_short_d16_hi v[22:23], v34, off
	s_waitcnt lgkmcnt(3)
	v_add_f32_e32 v21, 0, v26
	s_waitcnt lgkmcnt(2)
	v_add_f32_e32 v21, v21, v28
	s_waitcnt lgkmcnt(1)
	v_add_f32_e32 v21, v21, v30
	s_waitcnt lgkmcnt(0)
	v_add_f32_e32 v21, v21, v32
	v_add_u32_e32 v22, 0x12000, v57
	v_add_u32_e32 v23, 0x16000, v57
	v_add_u32_e32 v26, 0x1a000, v57
	v_add_u32_e32 v28, 0x1e000, v57
	v_add_u32_e32 v30, 0x12800, v57
	v_add_u32_e32 v32, 0x16800, v57
	v_add_u32_e32 v34, 0x1a800, v57
	v_add_u32_e32 v35, 0x1e800, v57
	ds_read_b32 v22, v22
	ds_read_b32 v23, v23
	ds_read_b32 v26, v26
	ds_read_b32 v28, v28
	ds_read_b32 v30, v30
	ds_read_b32 v32, v32
	ds_read_b32 v34, v34
	ds_read_b32 v35, v35
	s_waitcnt lgkmcnt(7)
	v_add_f32_e32 v21, v21, v22
	s_waitcnt lgkmcnt(6)
	v_add_f32_e32 v21, v21, v23
	s_waitcnt lgkmcnt(5)
	v_add_f32_e32 v21, v21, v26
	s_waitcnt lgkmcnt(4)
	v_add_f32_e32 v21, v21, v28
	s_waitcnt vmcnt(7)
	v_lshlrev_b32_e32 v22, 16, v60
	v_add_f32_e32 v21, v21, v22
	v_bfe_u32 v22, v21, 16, 1
	v_add3_u32 v22, v21, v22, s51
	global_store_short_d16_hi v[16:17], v22, off
	v_add_f32_e32 v16, 0, v27
	v_add_f32_e32 v16, v16, v29
	v_add_f32_e32 v16, v16, v31
	v_add_f32_e32 v16, v16, v33
	s_waitcnt lgkmcnt(3)
	v_add_f32_e32 v16, v16, v30
	s_waitcnt lgkmcnt(2)
	v_add_f32_e32 v16, v16, v32
	s_waitcnt lgkmcnt(1)
	v_add_f32_e32 v16, v16, v34
	s_waitcnt lgkmcnt(0)
	v_add_f32_e32 v16, v16, v35
	s_waitcnt vmcnt(7)
	v_lshlrev_b32_e32 v22, 16, v36
	v_add_f32_e32 v16, v16, v22
	v_bfe_u32 v22, v16, 16, 1
	v_add3_u32 v32, v16, v22, s51
	ds_read2st64_b32 v[22:23], v57 offset0:48 offset1:56
	ds_read2st64_b32 v[26:27], v57 offset0:112 offset1:120
	ds_read2st64_b32 v[28:29], v57 offset0:176 offset1:184
	ds_read2st64_b32 v[30:31], v57 offset0:240 offset1:248
	v_or_b32_e32 v17, v68, v54
	v_lshlrev_b32_e32 v196, 1, v17
	s_waitcnt lgkmcnt(3)
	v_add_f32_e32 v17, 0, v22
	s_waitcnt lgkmcnt(2)
	v_add_f32_e32 v17, v17, v26
	v_lshl_add_u64 v[18:19], v[18:19], 0, v[196:197]
	s_waitcnt lgkmcnt(1)
	v_add_f32_e32 v17, v17, v28
	global_store_short_d16_hi v[18:19], v32, off
	s_waitcnt lgkmcnt(0)
	v_add_f32_e32 v17, v17, v30
	v_add_u32_e32 v18, 0x13000, v57
	v_add_u32_e32 v19, 0x17000, v57
	v_add_u32_e32 v22, 0x1b000, v57
	v_add_u32_e32 v26, 0x1f000, v57
	v_add_u32_e32 v28, 0x13800, v57
	v_add_u32_e32 v30, 0x17800, v57
	v_add_u32_e32 v32, 0x1b800, v57
	v_add_u32_e32 v33, 0x1f800, v57
	ds_read_b32 v18, v18
	ds_read_b32 v19, v19
	ds_read_b32 v22, v22
	ds_read_b32 v26, v26
	ds_read_b32 v28, v28
	ds_read_b32 v30, v30
	ds_read_b32 v32, v32
	ds_read_b32 v33, v33
	s_waitcnt lgkmcnt(7)
	v_add_f32_e32 v17, v17, v18
	s_waitcnt lgkmcnt(6)
	v_add_f32_e32 v17, v17, v19
	s_waitcnt lgkmcnt(5)
	v_add_f32_e32 v17, v17, v22
	s_waitcnt lgkmcnt(4)
	v_add_f32_e32 v17, v17, v26
	s_waitcnt vmcnt(7)
	v_lshlrev_b32_e32 v19, 16, v37
	v_or_b32_e32 v18, v68, v55
	v_add_f32_e32 v17, v17, v19
	v_bfe_u32 v19, v17, 16, 1
	v_lshlrev_b32_e32 v196, 1, v18
	v_add3_u32 v19, v17, v19, s51
	v_lshl_add_u64 v[14:15], v[14:15], 0, v[196:197]
	global_store_short_d16_hi v[14:15], v19, off
	v_add_f32_e32 v14, 0, v23
	v_add_f32_e32 v14, v14, v27
	v_and_b32_e32 v19, 64, v239
	v_add_f32_e32 v15, v14, v29
	v_mul_f32_e32 v18, v25, v25
	v_xor_b32_e32 v14, 1, v239
	v_add_u32_e32 v25, 64, v19
	v_cmp_lt_i32_e32 vcc, v14, v25
	v_fmac_f32_e32 v18, v40, v40
	v_add_f32_e32 v15, v15, v31
	v_cndmask_b32_e32 v14, v239, v14, vcc
	v_lshlrev_b32_e32 v14, 2, v14
	ds_bpermute_b32 v19, v14, v18
	s_waitcnt lgkmcnt(4)
	v_add_f32_e32 v15, v15, v28
	s_waitcnt lgkmcnt(3)
	v_add_f32_e32 v15, v15, v30
	s_waitcnt lgkmcnt(2)
	v_add_f32_e32 v22, v15, v32
	v_xor_b32_e32 v15, 2, v239
	v_cmp_lt_i32_e32 vcc, v15, v25
	s_waitcnt lgkmcnt(0)
	v_add_f32_e32 v18, v18, v19
	v_add_f32_e32 v19, v22, v33
	v_cndmask_b32_e32 v15, v239, v15, vcc
	v_lshlrev_b32_e32 v15, 2, v15
	ds_bpermute_b32 v23, v15, v18
	s_waitcnt vmcnt(7)
	v_lshlrev_b32_e32 v22, 16, v38
	v_add_f32_e32 v19, v19, v22
	v_bfe_u32 v22, v19, 16, 1
	v_add3_u32 v29, v19, v22, s51
	s_waitcnt lgkmcnt(0)
	v_add_f32_e32 v27, v18, v23
	v_xor_b32_e32 v18, 4, v239
	v_cmp_lt_i32_e32 vcc, v18, v25
	v_lshl_add_u64 v[22:23], s[0:1], 0, v[12:13]
	v_xor_b32_e32 v12, 8, v239
	v_cndmask_b32_e32 v18, v239, v18, vcc
	v_lshlrev_b32_e32 v18, 2, v18
	ds_bpermute_b32 v28, v18, v27
	v_cmp_lt_i32_e32 vcc, v12, v25
	v_or_b32_e32 v26, v68, v56
	v_lshlrev_b32_e32 v196, 1, v26
	v_cndmask_b32_e32 v12, v239, v12, vcc
	s_waitcnt lgkmcnt(0)
	v_add_f32_e32 v13, v27, v28
	v_lshlrev_b32_e32 v12, 2, v12
	ds_bpermute_b32 v26, v12, v13
	v_cmp_eq_u32_e32 vcc, 0, v3
	v_xor_b32_e32 v3, 16, v239
	v_cmp_lt_i32_e64 s[0:1], v3, v25
	v_lshl_add_u64 v[22:23], v[22:23], 0, v[196:197]
	s_waitcnt lgkmcnt(0)
	v_add_f32_e32 v13, v13, v26
	v_cndmask_b32_e64 v3, v239, v3, s[0:1]
	v_lshlrev_b32_e32 v3, 2, v3
	global_store_short_d16_hi v[22:23], v29, off
	ds_bpermute_b32 v22, v3, v13
	s_add_u32 s0, s12, s8
	s_addc_u32 s1, s13, 0
	s_add_u32 s0, s0, 0x24100000
	s_addc_u32 s1, s1, 0
	s_and_saveexec_b64 s[8:9], vcc
	s_cbranch_execz .LBB0_859
	v_lshlrev_b64 v[6:7], 6, v[6:7]
	v_lshl_add_u64 v[6:7], s[0:1], 0, v[6:7]
	s_waitcnt lgkmcnt(0)
	v_add_f32_e32 v13, v13, v22
	global_store_dword v[6:7], v13, off

; #define LAS __attribute__((address_space(3)))
; __device__ __forceinline__ int fresh_tid() { int t = threadIdx.x; asm volatile("" : "+v"(t)); return t; }
; template <int K>
; __device__ __forceinline__ void piece(LAS unsigned char* lds, int p, const bf16* A  , const bf16* Bt, bf16* xb  , float* rowsq  ) {
;     const int tid = fresh_tid(), wid = __builtin_amdgcn_readfirstlane(tid >> 6), lane = tid & 63, r = lane & 31, hh = lane >> 5;
;     const int r0 = (p >> 4) * 64, c0 = (p & 15) * 64;
;     constexpr int KW = K / 8, NS = KW / 16;
;     static_assert(KW % 16 == 0, "K / 8 must be a multiple of 16");
;     const bf16* ap = A + (size_t)(r0 + r) * K + wid * KW + 8 * hh; const bf16* bp = Bt + (size_t)(c0 + r) * K + wid * KW + 8 * hh;
;     f32x16 acc[2][2] = {};
;     constexpr int U = (NS % 11 == 0) ? 11 : 8;
;     static_assert(NS % U == 0, "batching");
;     for (int kb = 0; kb < NS; kb += U) {
;         bf16x8 a0[U], a1[U], b0[U], b1[U];
; #pragma unroll
;         for (int u = 0; u < U; ++u) { a0[u] = *(const bf16x8*)(ap + (kb + u) * 16); a1[u] = *(const bf16x8*)(ap + (size_t)32 * K + (kb + u) * 16);
;                                       b0[u] = *(const bf16x8*)(bp + (kb + u) * 16); b1[u] = *(const bf16x8*)(bp + (size_t)32 * K + (kb + u) * 16); }
; #pragma unroll
;         for (int u = 0; u < U; ++u) {
;             acc[0][0] = __builtin_amdgcn_mfma_f32_32x32x16_bf16(a0[u], b0[u], acc[0][0], 0, 0, 0); acc[0][1] = __builtin_amdgcn_mfma_f32_32x32x16_bf16(a0[u], b1[u], acc[0][1], 0, 0, 0);
;             acc[1][0] = __builtin_amdgcn_mfma_f32_32x32x16_bf16(a1[u], b0[u], acc[1][0], 0, 0, 0); acc[1][1] = __builtin_amdgcn_mfma_f32_32x32x16_bf16(a1[u], b1[u], acc[1][1], 0, 0, 0); }
.LBB0_1035:
	v_mov_b32_e32 v3, 0x20258
	v_mov_b32_e32 v6, 0x20258
	v_add_u32_e32 v3, 0, v3
	ds_read_b32 v4, v3
	ds_read_b32 v3, v3 offset:4
	v_mov_b32_e32 v7, 0x20258
	v_mov_b32_e32 v77, v0
	s_waitcnt lgkmcnt(1)
	v_readfirstlane_b32 s0, v4
	s_waitcnt lgkmcnt(0)
	v_readfirstlane_b32 s1, v3
	v_add_u32_e32 v3, 0, v6
	ds_read_b32 v6, v3
	ds_read_b32 v3, v3 offset:4
	v_mov_b32_e32 v4, s0
	v_add_u32_e32 v7, 0, v7
	ds_read_b32 v8, v7
	s_waitcnt lgkmcnt(2)
	v_readfirstlane_b32 s0, v6
	v_mov_b32_e32 v6, 0x20258
	v_mov_b32_e32 v5, s1
	s_waitcnt lgkmcnt(1)
	v_readfirstlane_b32 s1, v3
	ds_read_b32 v3, v7 offset:4
	s_add_u32 s12, s0, s43
	v_add_u32_e32 v6, 0, v6
	ds_read_b32 v7, v6
	ds_read_b32 v6, v6 offset:4
	s_addc_u32 s13, s1, s42
	s_waitcnt lgkmcnt(3)
	v_readfirstlane_b32 s0, v8
	s_waitcnt lgkmcnt(2)
	v_readfirstlane_b32 s1, v3
	s_add_u32 s0, s0, 0xcc00000
	s_addc_u32 s1, s1, 0
	s_waitcnt lgkmcnt(1)
	v_readfirstlane_b32 s4, v7
	s_waitcnt lgkmcnt(0)
	v_readfirstlane_b32 s5, v6
	s_add_u32 s8, s4, s26
	s_addc_u32 s9, s5, 0
	v_readfirstlane_b32 s4, v77
	s_ashr_i32 s5, s4, 6
	v_and_b32_e32 v3, 31, v77
	s_and_b32 s4, s6, 0xffffffc0
	v_or_b32_e32 v6, s4, v3
	s_movk_i32 s11, 0x1600
	v_mad_i64_i32 v[4:5], s[14:15], v6, s11, v[4:5]
	s_mul_i32 s14, s5, 0x160
	s_ashr_i32 s15, s14, 31
	s_and_b32 s10, s7, 15
	s_lshl_b64 s[14:15], s[14:15], 1
	v_lshrrev_b32_e32 v6, 1, v77
	v_lshl_add_u64 v[4:5], v[4:5], 0, s[14:15]
	v_and_b32_e32 v196, 16, v6
	v_lshl_or_b32 v76, s10, 6, v3
	v_lshl_add_u64 v[44:45], v[4:5], 0, v[196:197]
	v_mul_u32_u24_e32 v4, 0xb00, v76
	v_lshlrev_b32_e32 v4, 1, v4
	v_mov_b32_e32 v5, v197
	v_lshl_add_u64 v[4:5], s[12:13], 0, v[4:5]
	v_lshl_add_u64 v[4:5], v[4:5], 0, s[14:15]
	s_mov_b32 s11, 0x1b700000
	v_lshl_add_u64 v[46:47], v[4:5], 0, v[196:197]
	v_add_co_u32_e32 v4, vcc, s11, v44
	s_mov_b64 s[12:13], 0x1b700000
	s_nop 0
	v_addc_co_u32_e32 v5, vcc, 0, v45, vcc
	s_mov_b32 s11, 0x1580000
	v_lshl_add_u64 v[72:73], v[44:45], 0, s[12:13]
	v_add_co_u32_e32 v4, vcc, s11, v46
	s_mov_b32 s11, 0x15ac000
	s_nop 0
	v_addc_co_u32_e32 v5, vcc, 0, v47, vcc
	v_add_co_u32_e32 v68, vcc, s11, v46
	s_nop 0
	v_addc_co_u32_e32 v69, vcc, 0, v47, vcc
	s_mov_b64 s[12:13], 0x1580000
	v_lshl_add_u64 v[74:75], v[46:47], 0, s[12:13]
	s_mov_b32 s11, 0x1b72c000
	v_add_co_u32_e32 v70, vcc, s11, v44
	s_lshl_b32 s5, s5, 14
	s_nop 0
	v_addc_co_u32_e32 v71, vcc, 0, v45, vcc
	s_add_i32 s5, s5, 0
	global_load_dwordx4 v[98:101], v[72:73], off
	global_load_dwordx4 v[106:109], v[74:75], off
	global_load_dwordx4 v[110:113], v[68:69], off
	global_load_dwordx4 v[102:105], v[70:71], off
	global_load_dwordx4 v[114:117], v[72:73], off offset:32
	global_load_dwordx4 v[122:125], v[74:75], off offset:32
	global_load_dwordx4 v[126:129], v[68:69], off offset:32
	global_load_dwordx4 v[118:121], v[70:71], off offset:32
	global_load_dwordx4 v[130:133], v[72:73], off offset:64
	global_load_dwordx4 v[138:141], v[74:75], off offset:64
	global_load_dwordx4 v[142:145], v[68:69], off offset:64
	global_load_dwordx4 v[134:137], v[70:71], off offset:64
	global_load_dwordx4 v[146:149], v[72:73], off offset:96
	global_load_dwordx4 v[154:157], v[74:75], off offset:96
	global_load_dwordx4 v[158:161], v[68:69], off offset:96
	global_load_dwordx4 v[150:153], v[70:71], off offset:96
	global_load_dwordx4 v[162:165], v[72:73], off offset:128
	global_load_dwordx4 v[170:173], v[74:75], off offset:128
	global_load_dwordx4 v[174:177], v[68:69], off offset:128
	global_load_dwordx4 v[166:169], v[70:71], off offset:128
	global_load_dwordx4 v[178:181], v[72:73], off offset:160
	global_load_dwordx4 v[186:189], v[74:75], off offset:160
	global_load_dwordx4 v[190:193], v[68:69], off offset:160
	global_load_dwordx4 v[182:185], v[70:71], off offset:160
	global_load_dwordx4 v[210:213], v[72:73], off offset:192
	global_load_dwordx4 v[218:221], v[74:75], off offset:192
	global_load_dwordx4 v[222:225], v[68:69], off offset:192
	global_load_dwordx4 v[214:217], v[70:71], off offset:192
	global_load_dwordx4 v[78:81], v[72:73], off offset:224
	global_load_dwordx4 v[86:89], v[74:75], off offset:224
	global_load_dwordx4 v[90:93], v[68:69], off offset:224
	global_load_dwordx4 v[82:85], v[70:71], off offset:224
	s_waitcnt vmcnt(30)
	v_mfma_f32_32x32x16_bf16 v[4:19], v[98:101], v[106:109], 0
	s_waitcnt vmcnt(29)
	v_mfma_f32_32x32x16_bf16 v[52:67], v[98:101], v[110:113], 0
	s_waitcnt vmcnt(28)
	v_mfma_f32_32x32x16_bf16 v[20:35], v[102:105], v[106:109], 0
	v_mfma_f32_32x32x16_bf16 v[36:51], v[102:105], v[110:113], 0
	global_load_dwordx4 v[98:101], v[72:73], off offset:256
	global_load_dwordx4 v[106:109], v[74:75], off offset:256
	global_load_dwordx4 v[110:113], v[68:69], off offset:256
	global_load_dwordx4 v[102:105], v[70:71], off offset:256
	s_waitcnt vmcnt(30)
	v_mfma_f32_32x32x16_bf16 v[4:19], v[114:117], v[122:125], v[4:19]
	s_waitcnt vmcnt(29)
	v_mfma_f32_32x32x16_bf16 v[52:67], v[114:117], v[126:129], v[52:67]
	s_waitcnt vmcnt(28)
	v_mfma_f32_32x32x16_bf16 v[20:35], v[118:121], v[122:125], v[20:35]
	v_mfma_f32_32x32x16_bf16 v[36:51], v[118:121], v[126:129], v[36:51]
	global_load_dwordx4 v[114:117], v[72:73], off offset:288
	global_load_dwordx4 v[122:125], v[74:75], off offset:288
	global_load_dwordx4 v[126:129], v[68:69], off offset:288
	global_load_dwordx4 v[118:121], v[70:71], off offset:288
	s_waitcnt vmcnt(30)
	v_mfma_f32_32x32x16_bf16 v[4:19], v[130:133], v[138:141], v[4:19]
	s_waitcnt vmcnt(29)
	v_mfma_f32_32x32x16_bf16 v[52:67], v[130:133], v[142:145], v[52:67]
	s_waitcnt vmcnt(28)
; template <int K>
; __device__ __forceinline__ void piece(LAS unsigned char* lds, int p, const bf16* A  , const bf16* Bt, bf16* xb  , float* rowsq  ) {
;     ...
;     for (int kb = 0; kb < NS; kb += U) {
;         bf16x8 a0[U], a1[U], b0[U], b1[U];
; #pragma unroll
;         for (int u = 0; u < U; ++u) { a0[u] = *(const bf16x8*)(ap + (kb + u) * 16); a1[u] = *(const bf16x8*)(ap + (size_t)32 * K + (kb + u) * 16);
;                                       b0[u] = *(const bf16x8*)(bp + (kb + u) * 16); b1[u] = *(const bf16x8*)(bp + (size_t)32 * K + (kb + u) * 16); }
; #pragma unroll
;         for (int u = 0; u < U; ++u) {
;             acc[0][0] = __builtin_amdgcn_mfma_f32_32x32x16_bf16(a0[u], b0[u], acc[0][0], 0, 0, 0); acc[0][1] = __builtin_amdgcn_mfma_f32_32x32x16_bf16(a0[u], b1[u], acc[0][1], 0, 0, 0);
;             acc[1][0] = __builtin_amdgcn_mfma_f32_32x32x16_bf16(a1[u], b0[u], acc[1][0], 0, 0, 0); acc[1][1] = __builtin_amdgcn_mfma_f32_32x32x16_bf16(a1[u], b1[u], acc[1][1], 0, 0, 0); }
	v_mfma_f32_32x32x16_bf16 v[20:35], v[134:137], v[138:141], v[20:35]
	v_mfma_f32_32x32x16_bf16 v[36:51], v[134:137], v[142:145], v[36:51]
	global_load_dwordx4 v[130:133], v[72:73], off offset:320
	global_load_dwordx4 v[138:141], v[74:75], off offset:320
	global_load_dwordx4 v[142:145], v[68:69], off offset:320
	global_load_dwordx4 v[134:137], v[70:71], off offset:320
	s_waitcnt vmcnt(30)
	v_mfma_f32_32x32x16_bf16 v[4:19], v[146:149], v[154:157], v[4:19]
	s_waitcnt vmcnt(29)
	v_mfma_f32_32x32x16_bf16 v[52:67], v[146:149], v[158:161], v[52:67]
	s_waitcnt vmcnt(28)
	v_mfma_f32_32x32x16_bf16 v[20:35], v[150:153], v[154:157], v[20:35]
	v_mfma_f32_32x32x16_bf16 v[36:51], v[150:153], v[158:161], v[36:51]
	global_load_dwordx4 v[146:149], v[72:73], off offset:352
	global_load_dwordx4 v[154:157], v[74:75], off offset:352
	global_load_dwordx4 v[158:161], v[68:69], off offset:352
	global_load_dwordx4 v[150:153], v[70:71], off offset:352
	s_waitcnt vmcnt(30)
	v_mfma_f32_32x32x16_bf16 v[4:19], v[162:165], v[170:173], v[4:19]
	s_waitcnt vmcnt(29)
	v_mfma_f32_32x32x16_bf16 v[52:67], v[162:165], v[174:177], v[52:67]
	s_waitcnt vmcnt(28)
	v_mfma_f32_32x32x16_bf16 v[20:35], v[166:169], v[170:173], v[20:35]
	v_mfma_f32_32x32x16_bf16 v[36:51], v[166:169], v[174:177], v[36:51]
	global_load_dwordx4 v[162:165], v[72:73], off offset:384
	global_load_dwordx4 v[170:173], v[74:75], off offset:384
	global_load_dwordx4 v[174:177], v[68:69], off offset:384
	global_load_dwordx4 v[166:169], v[70:71], off offset:384
	s_waitcnt vmcnt(30)
	v_mfma_f32_32x32x16_bf16 v[4:19], v[178:181], v[186:189], v[4:19]
	s_waitcnt vmcnt(29)
	v_mfma_f32_32x32x16_bf16 v[52:67], v[178:181], v[190:193], v[52:67]
	s_waitcnt vmcnt(28)
	v_mfma_f32_32x32x16_bf16 v[20:35], v[182:185], v[186:189], v[20:35]
	v_mfma_f32_32x32x16_bf16 v[36:51], v[182:185], v[190:193], v[36:51]
	global_load_dwordx4 v[178:181], v[72:73], off offset:416
	global_load_dwordx4 v[186:189], v[74:75], off offset:416
	global_load_dwordx4 v[190:193], v[68:69], off offset:416
	global_load_dwordx4 v[182:185], v[70:71], off offset:416
	s_waitcnt vmcnt(30)
	v_mfma_f32_32x32x16_bf16 v[4:19], v[210:213], v[218:221], v[4:19]
	s_waitcnt vmcnt(29)
	v_mfma_f32_32x32x16_bf16 v[52:67], v[210:213], v[222:225], v[52:67]
	s_waitcnt vmcnt(28)
	v_mfma_f32_32x32x16_bf16 v[20:35], v[214:217], v[218:221], v[20:35]
	v_mfma_f32_32x32x16_bf16 v[36:51], v[214:217], v[222:225], v[36:51]
	global_load_dwordx4 v[210:213], v[72:73], off offset:448
	global_load_dwordx4 v[218:221], v[74:75], off offset:448
	global_load_dwordx4 v[222:225], v[68:69], off offset:448
	global_load_dwordx4 v[214:217], v[70:71], off offset:448
	s_waitcnt vmcnt(30)
	v_mfma_f32_32x32x16_bf16 v[4:19], v[78:81], v[86:89], v[4:19]
	s_waitcnt vmcnt(29)
	v_mfma_f32_32x32x16_bf16 v[52:67], v[78:81], v[90:93], v[52:67]
	s_waitcnt vmcnt(28)
	v_mfma_f32_32x32x16_bf16 v[20:35], v[82:85], v[86:89], v[20:35]
	v_mfma_f32_32x32x16_bf16 v[36:51], v[82:85], v[90:93], v[36:51]
	global_load_dwordx4 v[78:81], v[72:73], off offset:480
	global_load_dwordx4 v[86:89], v[74:75], off offset:480
	global_load_dwordx4 v[90:93], v[68:69], off offset:480
	global_load_dwordx4 v[82:85], v[70:71], off offset:480
	s_waitcnt vmcnt(30)
	v_mfma_f32_32x32x16_bf16 v[4:19], v[98:101], v[106:109], v[4:19]
	s_waitcnt vmcnt(29)
	v_mfma_f32_32x32x16_bf16 v[52:67], v[98:101], v[110:113], v[52:67]
	s_waitcnt vmcnt(28)
	v_mfma_f32_32x32x16_bf16 v[20:35], v[102:105], v[106:109], v[20:35]
	v_mfma_f32_32x32x16_bf16 v[36:51], v[102:105], v[110:113], v[36:51]
	global_load_dwordx4 v[98:101], v[72:73], off offset:512
	global_load_dwordx4 v[106:109], v[74:75], off offset:512
	global_load_dwordx4 v[110:113], v[68:69], off offset:512
	global_load_dwordx4 v[102:105], v[70:71], off offset:512
	s_waitcnt vmcnt(30)
	v_mfma_f32_32x32x16_bf16 v[4:19], v[114:117], v[122:125], v[4:19]
	s_waitcnt vmcnt(29)
	v_mfma_f32_32x32x16_bf16 v[52:67], v[114:117], v[126:129], v[52:67]
	s_waitcnt vmcnt(28)
	v_mfma_f32_32x32x16_bf16 v[20:35], v[118:121], v[122:125], v[20:35]
	v_mfma_f32_32x32x16_bf16 v[36:51], v[118:121], v[126:129], v[36:51]
	global_load_dwordx4 v[114:117], v[72:73], off offset:544
	global_load_dwordx4 v[122:125], v[74:75], off offset:544
	global_load_dwordx4 v[126:129], v[68:69], off offset:544
	global_load_dwordx4 v[118:121], v[70:71], off offset:544
	s_waitcnt vmcnt(30)
	v_mfma_f32_32x32x16_bf16 v[4:19], v[130:133], v[138:141], v[4:19]
	s_waitcnt vmcnt(29)
	v_mfma_f32_32x32x16_bf16 v[52:67], v[130:133], v[142:145], v[52:67]
	s_waitcnt vmcnt(28)
	v_mfma_f32_32x32x16_bf16 v[20:35], v[134:137], v[138:141], v[20:35]
	v_mfma_f32_32x32x16_bf16 v[36:51], v[134:137], v[142:145], v[36:51]
	global_load_dwordx4 v[130:133], v[72:73], off offset:576
	global_load_dwordx4 v[138:141], v[74:75], off offset:576
	global_load_dwordx4 v[142:145], v[68:69], off offset:576
	global_load_dwordx4 v[134:137], v[70:71], off offset:576
	s_waitcnt vmcnt(30)
	v_mfma_f32_32x32x16_bf16 v[4:19], v[146:149], v[154:157], v[4:19]
	s_waitcnt vmcnt(29)
	v_mfma_f32_32x32x16_bf16 v[52:67], v[146:149], v[158:161], v[52:67]
	s_waitcnt vmcnt(28)
	v_mfma_f32_32x32x16_bf16 v[20:35], v[150:153], v[154:157], v[20:35]
	v_mfma_f32_32x32x16_bf16 v[36:51], v[150:153], v[158:161], v[36:51]
	global_load_dwordx4 v[146:149], v[72:73], off offset:608
	global_load_dwordx4 v[154:157], v[74:75], off offset:608
	global_load_dwordx4 v[158:161], v[68:69], off offset:608
	global_load_dwordx4 v[150:153], v[70:71], off offset:608
	s_waitcnt vmcnt(30)
	v_mfma_f32_32x32x16_bf16 v[4:19], v[162:165], v[170:173], v[4:19]
	s_waitcnt vmcnt(29)
	v_mfma_f32_32x32x16_bf16 v[52:67], v[162:165], v[174:177], v[52:67]
	s_waitcnt vmcnt(28)
; #define LAS __attribute__((address_space(3)))
; template <int K>
; __device__ __forceinline__ void piece(LAS unsigned char* lds, int p, const bf16* A  , const bf16* Bt, bf16* xb  , float* rowsq  ) {
;     ...
;         for (int u = 0; u < U; ++u) {
;             acc[0][0] = __builtin_amdgcn_mfma_f32_32x32x16_bf16(a0[u], b0[u], acc[0][0], 0, 0, 0); acc[0][1] = __builtin_amdgcn_mfma_f32_32x32x16_bf16(a0[u], b1[u], acc[0][1], 0, 0, 0);
;             acc[1][0] = __builtin_amdgcn_mfma_f32_32x32x16_bf16(a1[u], b0[u], acc[1][0], 0, 0, 0); acc[1][1] = __builtin_amdgcn_mfma_f32_32x32x16_bf16(a1[u], b1[u], acc[1][1], 0, 0, 0); }
;     }
;     LAS float* P = (LAS float*)lds;
; #pragma unroll
;     for (int i = 0; i < 2; ++i)
; #pragma unroll
;         for (int j = 0; j < 2; ++j)
; #pragma unroll
;             for (int q = 0; q < 16; ++q) P[(((wid * 2 + i) * 2 + j) * 16 + q) * 64 + lane] = acc[i][j][q];
;     __syncthreads();
	v_mfma_f32_32x32x16_bf16 v[20:35], v[166:169], v[170:173], v[20:35]
	v_mfma_f32_32x32x16_bf16 v[36:51], v[166:169], v[174:177], v[36:51]
	global_load_dwordx4 v[162:165], v[72:73], off offset:640
	global_load_dwordx4 v[170:173], v[74:75], off offset:640
	global_load_dwordx4 v[174:177], v[68:69], off offset:640
	global_load_dwordx4 v[166:169], v[70:71], off offset:640
	s_waitcnt vmcnt(30)
	v_mfma_f32_32x32x16_bf16 v[4:19], v[178:181], v[186:189], v[4:19]
	s_waitcnt vmcnt(29)
	v_mfma_f32_32x32x16_bf16 v[52:67], v[178:181], v[190:193], v[52:67]
	s_waitcnt vmcnt(28)
	v_mfma_f32_32x32x16_bf16 v[20:35], v[182:185], v[186:189], v[20:35]
	v_mfma_f32_32x32x16_bf16 v[36:51], v[182:185], v[190:193], v[36:51]
	global_load_dwordx4 v[178:181], v[72:73], off offset:672
	global_load_dwordx4 v[186:189], v[74:75], off offset:672
	global_load_dwordx4 v[190:193], v[68:69], off offset:672
	global_load_dwordx4 v[182:185], v[70:71], off offset:672
	s_waitcnt vmcnt(30)
	v_mfma_f32_32x32x16_bf16 v[4:19], v[210:213], v[218:221], v[4:19]
	s_waitcnt vmcnt(29)
	v_mfma_f32_32x32x16_bf16 v[52:67], v[210:213], v[222:225], v[52:67]
	s_waitcnt vmcnt(28)
	v_mfma_f32_32x32x16_bf16 v[20:35], v[214:217], v[218:221], v[20:35]
	v_mfma_f32_32x32x16_bf16 v[36:51], v[214:217], v[222:225], v[36:51]
	s_waitcnt vmcnt(26)
	v_mfma_f32_32x32x16_bf16 v[4:19], v[78:81], v[86:89], v[4:19]
	s_waitcnt vmcnt(25)
	v_mfma_f32_32x32x16_bf16 v[52:67], v[78:81], v[90:93], v[52:67]
	s_waitcnt vmcnt(24)
	v_mfma_f32_32x32x16_bf16 v[20:35], v[82:85], v[86:89], v[20:35]
	v_mfma_f32_32x32x16_bf16 v[36:51], v[82:85], v[90:93], v[36:51]
	s_waitcnt vmcnt(22)
	v_mfma_f32_32x32x16_bf16 v[4:19], v[98:101], v[106:109], v[4:19]
	s_waitcnt vmcnt(21)
	v_mfma_f32_32x32x16_bf16 v[52:67], v[98:101], v[110:113], v[52:67]
	s_waitcnt vmcnt(20)
	v_mfma_f32_32x32x16_bf16 v[20:35], v[102:105], v[106:109], v[20:35]
	v_mfma_f32_32x32x16_bf16 v[36:51], v[102:105], v[110:113], v[36:51]
	s_waitcnt vmcnt(18)
	v_mfma_f32_32x32x16_bf16 v[4:19], v[114:117], v[122:125], v[4:19]
	s_waitcnt vmcnt(17)
	v_mfma_f32_32x32x16_bf16 v[52:67], v[114:117], v[126:129], v[52:67]
	s_waitcnt vmcnt(16)
	v_mfma_f32_32x32x16_bf16 v[20:35], v[118:121], v[122:125], v[20:35]
	v_mfma_f32_32x32x16_bf16 v[36:51], v[118:121], v[126:129], v[36:51]
	s_waitcnt vmcnt(14)
	v_mfma_f32_32x32x16_bf16 v[4:19], v[130:133], v[138:141], v[4:19]
	s_waitcnt vmcnt(13)
	v_mfma_f32_32x32x16_bf16 v[52:67], v[130:133], v[142:145], v[52:67]
	s_waitcnt vmcnt(12)
	v_mfma_f32_32x32x16_bf16 v[20:35], v[134:137], v[138:141], v[20:35]
	v_mfma_f32_32x32x16_bf16 v[36:51], v[134:137], v[142:145], v[36:51]
	s_waitcnt vmcnt(10)
	v_mfma_f32_32x32x16_bf16 v[4:19], v[146:149], v[154:157], v[4:19]
	s_waitcnt vmcnt(9)
	v_mfma_f32_32x32x16_bf16 v[52:67], v[146:149], v[158:161], v[52:67]
	s_waitcnt vmcnt(8)
	v_mfma_f32_32x32x16_bf16 v[20:35], v[150:153], v[154:157], v[20:35]
	v_mfma_f32_32x32x16_bf16 v[36:51], v[150:153], v[158:161], v[36:51]
	s_waitcnt vmcnt(6)
	v_mfma_f32_32x32x16_bf16 v[4:19], v[162:165], v[170:173], v[4:19]
	s_waitcnt vmcnt(5)
	v_mfma_f32_32x32x16_bf16 v[52:67], v[162:165], v[174:177], v[52:67]
	s_waitcnt vmcnt(4)
	v_mfma_f32_32x32x16_bf16 v[20:35], v[166:169], v[170:173], v[20:35]
	v_mfma_f32_32x32x16_bf16 v[36:51], v[166:169], v[174:177], v[36:51]
	s_waitcnt vmcnt(2)
	v_mfma_f32_32x32x16_bf16 v[4:19], v[178:181], v[186:189], v[4:19]
	s_waitcnt vmcnt(1)
	v_mfma_f32_32x32x16_bf16 v[52:67], v[178:181], v[190:193], v[52:67]
	s_waitcnt vmcnt(0)
	v_mfma_f32_32x32x16_bf16 v[20:35], v[182:185], v[186:189], v[20:35]
	v_mfma_f32_32x32x16_bf16 v[36:51], v[182:185], v[190:193], v[36:51]
	v_and_b32_e32 v82, 63, v77
	v_lshl_add_u32 v82, v82, 2, s5
	s_nop 11
	ds_write2st64_b32 v82, v4, v5 offset1:1
	ds_write2st64_b32 v82, v6, v7 offset0:2 offset1:3
	ds_write2st64_b32 v82, v8, v9 offset0:4 offset1:5
	v_lshrrev_b32_e32 v4, 3, v77
	ds_write2st64_b32 v82, v10, v11 offset0:6 offset1:7
	ds_write2st64_b32 v82, v12, v13 offset0:8 offset1:9
	ds_write2st64_b32 v82, v14, v15 offset0:10 offset1:11
	ds_write2st64_b32 v82, v16, v17 offset0:12 offset1:13
	ds_write2st64_b32 v82, v18, v19 offset0:14 offset1:15
	s_nop 5
	ds_write2st64_b32 v82, v52, v53 offset0:16 offset1:17
	ds_write2st64_b32 v82, v54, v55 offset0:18 offset1:19
	v_lshrrev_b32_e32 v8, 5, v77
	v_bfe_u32 v5, v77, 6, 2
	v_and_b32_e32 v6, 24, v8
	v_mov_b32_e32 v13, v197
	ds_write2st64_b32 v82, v56, v57 offset0:20 offset1:21
	ds_write2st64_b32 v82, v58, v59 offset0:22 offset1:23
	ds_write2st64_b32 v82, v60, v61 offset0:24 offset1:25
	ds_write2st64_b32 v82, v62, v63 offset0:26 offset1:27
	ds_write2st64_b32 v82, v64, v65 offset0:28 offset1:29
	ds_write2st64_b32 v82, v66, v67 offset0:30 offset1:31
	s_nop 5
	ds_write2st64_b32 v82, v20, v21 offset0:32 offset1:33
	ds_write2st64_b32 v82, v22, v23 offset0:34 offset1:35
	ds_write2st64_b32 v82, v24, v25 offset0:36 offset1:37
	ds_write2st64_b32 v82, v26, v27 offset0:38 offset1:39
	ds_write2st64_b32 v82, v28, v29 offset0:40 offset1:41
	ds_write2st64_b32 v82, v30, v31 offset0:42 offset1:43
	ds_write2st64_b32 v82, v32, v33 offset0:44 offset1:45
	ds_write2st64_b32 v82, v34, v35 offset0:46 offset1:47
	s_nop 11
	ds_write2st64_b32 v82, v36, v37 offset0:48 offset1:49
	ds_write2st64_b32 v82, v38, v39 offset0:50 offset1:51
	ds_write2st64_b32 v82, v40, v41 offset0:52 offset1:53
	ds_write2st64_b32 v82, v42, v43 offset0:54 offset1:55
	ds_write2st64_b32 v82, v44, v45 offset0:56 offset1:57
	ds_write2st64_b32 v82, v46, v47 offset0:58 offset1:59
	ds_write2st64_b32 v82, v48, v49 offset0:60 offset1:61
	ds_write2st64_b32 v82, v50, v51 offset0:62 offset1:63
	v_and_or_b32 v40, v4, 4, s4
	v_ashrrev_i32_e32 v4, 6, v77
	v_and_b32_e32 v4, 0xffffffe0, v4
	v_add_u32_e32 v4, v40, v4
	s_lshl_b32 s4, s10, 7
	v_or3_b32 v6, v4, v5, v6
	s_add_u32 s4, s0, s4
	v_ashrrev_i32_e32 v7, 31, v6
	s_addc_u32 s5, s1, 0
	v_and_b32_e32 v48, 32, v8
	v_lshlrev_b64 v[24:25], 11, v[6:7]
	v_lshl_add_u64 v[4:5], s[4:5], 0, v[24:25]
	v_lshlrev_b32_e32 v196, 1, v48
	v_lshl_add_u64 v[4:5], v[4:5], 0, v[196:197]
	v_lshlrev_b32_e32 v26, 1, v3
	v_mov_b32_e32 v27, v197
	v_lshl_add_u64 v[8:9], v[4:5], 0, v[26:27]
	v_add_u32_e32 v4, 0x200, v77
	v_ashrrev_i32_e32 v5, 6, v4
	v_and_b32_e32 v5, 0xffffffe0, v5
	v_lshrrev_b32_e32 v11, 5, v4
	v_bfe_u32 v10, v4, 6, 2
	v_and_b32_e32 v4, 24, v11
	v_add_u32_e32 v5, v40, v5
	v_or3_b32 v4, v5, v10, v4
	v_ashrrev_i32_e32 v5, 31, v4
	v_and_b32_e32 v49, 32, v11
	v_lshlrev_b64 v[28:29], 11, v[4:5]
	v_lshl_add_u64 v[10:11], s[4:5], 0, v[28:29]
	v_lshlrev_b32_e32 v12, 1, v49
	v_lshl_add_u64 v[10:11], v[10:11], 0, v[12:13]
	s_waitcnt lgkmcnt(0)
	s_barrier
; __device__ __forceinline__ unsigned f2bf(float f) { unsigned u = __builtin_bit_cast(unsigned, f); return (u + 0x7fffu + ((u >> 16) & 1u)) >> 16; }
; __device__ __forceinline__ int crow(int r, int hi) { return (r & 3) + 8 * (r >> 2) + 4 * hi; }
; __device__ __forceinline__ int crow(int r, int hi) { return (r & 3) + 8 * (r >> 2) + 4 * hi; }
; __device__ __forceinline__ int crow(int r, int hi) { return (r & 3) + 8 * (r >> 2) + 4 * hi; }
; template <int K>
; __device__ __forceinline__ void piece(LAS unsigned char* lds, int p, const bf16* A  , const bf16* Bt, bf16* xb  , float* rowsq  ) {
;     ...
;     float vv[8]; unsigned short xin[8];
; #pragma unroll
;     for (int q = 0; q < 8; ++q) { const int e = tid + 512 * q; const int ln = e & 63, reg = (e >> 6) & 15, j = (e >> 10) & 1, i = e >> 11;
;         xin[q] = xb[(size_t)(r0 + 32 * i + crow(reg, ln >> 5)) * 1024 + c0 + 32 * j + (ln & 31)]; }
; #pragma unroll
;     for (int q = 0; q < 8; ++q) { const int e = tid + 512 * q;
;         float s = 0.f;
; #pragma unroll
;         for (int w = 0; w < 8; ++w) s += P[w * 4096 + e];
;         const int ln = e & 63, reg = (e >> 6) & 15, j = (e >> 10) & 1, i = e >> 11;
;         const int row = r0 + 32 * i + crow(reg, ln >> 5), col = c0 + 32 * j + (ln & 31);
;         const float v = bf2f(xin[q]) + s;
;         xb[(size_t)row * 1024 + col] = (bf16)f2bf(v); vv[q] = v; }
	v_lshl_add_u64 v[10:11], v[10:11], 0, v[26:27]
	global_load_ushort v50, v[8:9], off
	global_load_ushort v51, v[10:11], off
	v_add_u32_e32 v8, 0x400, v77
	v_ashrrev_i32_e32 v9, 6, v8
	v_and_b32_e32 v9, 0xffffffe0, v9
	v_lshrrev_b32_e32 v11, 5, v8
	v_bfe_u32 v10, v8, 6, 2
	v_and_b32_e32 v8, 24, v11
	v_add_u32_e32 v9, v40, v9
	v_or3_b32 v8, v9, v10, v8
	v_ashrrev_i32_e32 v9, 31, v8
	v_and_b32_e32 v52, 32, v11
	v_lshlrev_b64 v[20:21], 11, v[8:9]
	v_lshl_add_u64 v[8:9], s[4:5], 0, v[20:21]
	v_lshlrev_b32_e32 v10, 1, v52
	v_mov_b32_e32 v11, v197
	v_lshl_add_u64 v[8:9], v[8:9], 0, v[10:11]
	v_lshl_add_u64 v[30:31], v[8:9], 0, v[26:27]
	v_add_u32_e32 v8, 0x600, v77
	v_ashrrev_i32_e32 v9, 6, v8
	v_and_b32_e32 v9, 0xffffffe0, v9
	v_lshrrev_b32_e32 v11, 5, v8
	v_bfe_u32 v10, v8, 6, 2
	v_and_b32_e32 v8, 24, v11
	v_add_u32_e32 v9, v40, v9
	v_or3_b32 v8, v9, v10, v8
	v_ashrrev_i32_e32 v9, 31, v8
	v_and_b32_e32 v53, 32, v11
	v_lshlrev_b64 v[22:23], 11, v[8:9]
	v_lshl_add_u64 v[8:9], s[4:5], 0, v[22:23]
	v_lshlrev_b32_e32 v10, 1, v53
	v_mov_b32_e32 v11, v197
	v_lshl_add_u64 v[8:9], v[8:9], 0, v[10:11]
	v_lshl_add_u64 v[32:33], v[8:9], 0, v[26:27]
	v_add_u32_e32 v8, 0x800, v77
	v_ashrrev_i32_e32 v9, 6, v8
	v_and_b32_e32 v9, 0xffffffe0, v9
	v_bfe_u32 v10, v8, 6, 2
	v_lshrrev_b32_e32 v8, 5, v8
	v_and_b32_e32 v8, 24, v8
	v_add_u32_e32 v9, v40, v9
	v_or3_b32 v10, v9, v10, v8
	v_ashrrev_i32_e32 v11, 31, v10
	v_lshlrev_b64 v[16:17], 11, v[10:11]
	v_lshl_add_u64 v[8:9], s[4:5], 0, v[16:17]
	v_lshl_add_u64 v[8:9], v[8:9], 0, v[196:197]
	v_lshl_add_u64 v[34:35], v[8:9], 0, v[26:27]
	v_add_u32_e32 v8, 0xa00, v77
	v_ashrrev_i32_e32 v9, 6, v8
	v_and_b32_e32 v9, 0xffffffe0, v9
	v_lshrrev_b32_e32 v13, 5, v8
	v_bfe_u32 v12, v8, 6, 2
	v_and_b32_e32 v8, 24, v13
	v_add_u32_e32 v9, v40, v9
	v_or3_b32 v8, v9, v12, v8
	v_ashrrev_i32_e32 v9, 31, v8
	v_and_b32_e32 v54, 32, v13
	v_lshlrev_b64 v[18:19], 11, v[8:9]
	v_lshl_add_u64 v[12:13], s[4:5], 0, v[18:19]
	v_lshlrev_b32_e32 v196, 1, v54
	v_lshl_add_u64 v[12:13], v[12:13], 0, v[196:197]
	v_lshl_add_u64 v[36:37], v[12:13], 0, v[26:27]
	v_add_u32_e32 v12, 0xc00, v77
	v_ashrrev_i32_e32 v13, 6, v12
	v_and_b32_e32 v13, 0xffffffe0, v13
	v_lshrrev_b32_e32 v15, 5, v12
	v_bfe_u32 v14, v12, 6, 2
	v_and_b32_e32 v12, 24, v15
	v_add_u32_e32 v13, v40, v13
	v_or3_b32 v12, v13, v14, v12
	v_ashrrev_i32_e32 v13, 31, v12
	v_and_b32_e32 v55, 32, v15
	v_lshlrev_b64 v[14:15], 11, v[12:13]
	v_lshl_add_u64 v[12:13], s[4:5], 0, v[14:15]
	v_lshlrev_b32_e32 v196, 1, v55
	v_lshl_add_u64 v[12:13], v[12:13], 0, v[196:197]
	v_lshl_add_u64 v[38:39], v[12:13], 0, v[26:27]
	v_add_u32_e32 v12, 0xe00, v77
	v_ashrrev_i32_e32 v13, 6, v12
	v_and_b32_e32 v13, 0xffffffe0, v13
	v_lshrrev_b32_e32 v42, 5, v12
	v_bfe_u32 v41, v12, 6, 2
	v_and_b32_e32 v12, 24, v42
	v_add_u32_e32 v13, v40, v13
	v_or3_b32 v12, v13, v41, v12
	v_ashrrev_i32_e32 v13, 31, v12
	v_and_b32_e32 v56, 32, v42
	v_lshlrev_b64 v[12:13], 11, v[12:13]
	v_lshl_add_u64 v[40:41], s[4:5], 0, v[12:13]
	v_lshlrev_b32_e32 v196, 1, v56
	v_lshl_add_u64 v[40:41], v[40:41], 0, v[196:197]
	v_lshl_add_u32 v57, v77, 2, 0
	v_lshl_add_u64 v[26:27], v[40:41], 0, v[26:27]
	ds_read2st64_b32 v[40:41], v57 offset1:8
	ds_read2st64_b32 v[42:43], v57 offset0:64 offset1:72
	ds_read2st64_b32 v[44:45], v57 offset0:128 offset1:136
	ds_read2st64_b32 v[46:47], v57 offset0:192 offset1:200
	global_load_ushort v58, v[30:31], off
	global_load_ushort v59, v[32:33], off
	global_load_ushort v60, v[34:35], off
	s_nop 0
	global_load_ushort v36, v[36:37], off
	s_nop 0
	global_load_ushort v37, v[38:39], off
	s_nop 0
	global_load_ushort v38, v[26:27], off
	s_waitcnt lgkmcnt(3)
	v_add_f32_e32 v26, 0, v40
	s_waitcnt lgkmcnt(2)
	v_add_f32_e32 v26, v26, v42
	s_waitcnt lgkmcnt(1)
	v_add_f32_e32 v26, v26, v44
	s_waitcnt lgkmcnt(0)
	v_add_f32_e32 v26, v26, v46
	v_add_u32_e32 v27, 0x10000, v57
	v_add_u32_e32 v30, 0x14000, v57
	v_add_u32_e32 v31, 0x18000, v57
	v_add_u32_e32 v32, 0x1c000, v57
	v_add_u32_e32 v33, 0x10800, v57
	v_add_u32_e32 v34, 0x14800, v57
	v_add_u32_e32 v35, 0x18800, v57
	v_add_u32_e32 v39, 0x1c800, v57
	ds_read_b32 v27, v27
	ds_read_b32 v30, v30
	ds_read_b32 v31, v31
	ds_read_b32 v32, v32
	ds_read_b32 v33, v33
	ds_read_b32 v34, v34
	ds_read_b32 v35, v35
	ds_read_b32 v39, v39
	s_waitcnt lgkmcnt(7)
	v_add_f32_e32 v26, v26, v27
	s_waitcnt lgkmcnt(6)
	v_add_f32_e32 v26, v26, v30
	s_waitcnt lgkmcnt(5)
	v_add_f32_e32 v26, v26, v31
	s_waitcnt lgkmcnt(4)
	v_add_f32_e32 v26, v26, v32
	s_waitcnt vmcnt(7)
	v_lshlrev_b32_e32 v30, 16, v50
	v_or_b32_e32 v27, v76, v48
	v_add_f32_e32 v40, v26, v30
	v_bfe_u32 v26, v40, 16, 1
	v_lshl_add_u64 v[24:25], s[0:1], 0, v[24:25]
	v_lshlrev_b32_e32 v196, 1, v27
	v_add3_u32 v26, v40, v26, s51
	v_lshl_add_u64 v[24:25], v[24:25], 0, v[196:197]
	global_store_short_d16_hi v[24:25], v26, off
	v_add_f32_e32 v24, 0, v41
	v_add_f32_e32 v24, v24, v43
	v_add_f32_e32 v24, v24, v45
	v_add_f32_e32 v24, v24, v47
	s_waitcnt lgkmcnt(3)
	v_add_f32_e32 v24, v24, v33
	s_waitcnt lgkmcnt(2)
	v_add_f32_e32 v24, v24, v34
	s_waitcnt lgkmcnt(1)
	v_add_f32_e32 v24, v24, v35
	s_waitcnt lgkmcnt(0)
	v_add_f32_e32 v24, v24, v39
	s_waitcnt vmcnt(7)
	v_lshlrev_b32_e32 v26, 16, v51
	v_add_f32_e32 v24, v24, v26
	v_or_b32_e32 v25, v76, v49
	v_bfe_u32 v26, v24, 16, 1
	v_add3_u32 v39, v24, v26, s51
	v_lshl_add_u64 v[26:27], s[0:1], 0, v[28:29]
	v_lshlrev_b32_e32 v28, 1, v25
	v_mov_b32_e32 v29, v197
	v_lshl_add_u64 v[26:27], v[26:27], 0, v[28:29]
	ds_read2st64_b32 v[28:29], v57 offset0:16 offset1:24
	ds_read2st64_b32 v[30:31], v57 offset0:80 offset1:88
	ds_read2st64_b32 v[32:33], v57 offset0:144 offset1:152
	ds_read2st64_b32 v[34:35], v57 offset0:208 offset1:216
	global_store_short_d16_hi v[26:27], v39, off
	s_waitcnt lgkmcnt(3)
; __device__ __forceinline__ unsigned f2bf(float f) { unsigned u = __builtin_bit_cast(unsigned, f); return (u + 0x7fffu + ((u >> 16) & 1u)) >> 16; }
; __device__ __forceinline__ int crow(int r, int hi) { return (r & 3) + 8 * (r >> 2) + 4 * hi; }
; __device__ __forceinline__ int crow(int r, int hi) { return (r & 3) + 8 * (r >> 2) + 4 * hi; }
; __device__ __forceinline__ int crow(int r, int hi) { return (r & 3) + 8 * (r >> 2) + 4 * hi; }
; template <int K>
; __device__ __forceinline__ void piece(LAS unsigned char* lds, int p, const bf16* A  , const bf16* Bt, bf16* xb  , float* rowsq  ) {
;     ...
; #pragma unroll
;     for (int q = 0; q < 8; ++q) { const int e = tid + 512 * q;
;         float s = 0.f;
; #pragma unroll
;         for (int w = 0; w < 8; ++w) s += P[w * 4096 + e];
;         const int ln = e & 63, reg = (e >> 6) & 15, j = (e >> 10) & 1, i = e >> 11;
;         const int row = r0 + 32 * i + crow(reg, ln >> 5), col = c0 + 32 * j + (ln & 31);
;         const float v = bf2f(xin[q]) + s;
;         xb[(size_t)row * 1024 + col] = (bf16)f2bf(v); vv[q] = v; }
	v_add_f32_e32 v25, 0, v28
	s_waitcnt lgkmcnt(2)
	v_add_f32_e32 v25, v25, v30
	s_waitcnt lgkmcnt(1)
	v_add_f32_e32 v25, v25, v32
	s_waitcnt lgkmcnt(0)
	v_add_f32_e32 v25, v25, v34
	v_add_u32_e32 v26, 0x11000, v57
	v_add_u32_e32 v27, 0x15000, v57
	v_add_u32_e32 v28, 0x19000, v57
	v_add_u32_e32 v30, 0x1d000, v57
	v_add_u32_e32 v32, 0x11800, v57
	v_add_u32_e32 v34, 0x15800, v57
	v_add_u32_e32 v39, 0x19800, v57
	v_add_u32_e32 v41, 0x1d800, v57
	ds_read_b32 v26, v26
	ds_read_b32 v27, v27
	ds_read_b32 v28, v28
	ds_read_b32 v30, v30
	ds_read_b32 v32, v32
	ds_read_b32 v34, v34
	ds_read_b32 v39, v39
	ds_read_b32 v41, v41
	s_waitcnt lgkmcnt(7)
	v_add_f32_e32 v25, v25, v26
	s_waitcnt lgkmcnt(6)
	v_add_f32_e32 v25, v25, v27
	s_waitcnt lgkmcnt(5)
	v_add_f32_e32 v25, v25, v28
	s_waitcnt lgkmcnt(4)
	v_add_f32_e32 v25, v25, v30
	v_or_b32_e32 v26, v76, v52
	v_lshl_add_u64 v[20:21], s[0:1], 0, v[20:21]
	v_lshlrev_b32_e32 v26, 1, v26
	v_lshl_add_u64 v[22:23], s[0:1], 0, v[22:23]
	v_lshl_add_u64 v[16:17], s[0:1], 0, v[16:17]
	v_lshl_add_u64 v[16:17], v[16:17], 0, v[196:197]
	v_lshl_add_u64 v[18:19], s[0:1], 0, v[18:19]
	v_lshl_add_u64 v[14:15], s[0:1], 0, v[14:15]
	s_lshl_b32 s4, s10, 2
	s_waitcnt vmcnt(7)
	v_lshlrev_b32_e32 v27, 16, v58
	v_add_f32_e32 v25, v25, v27
	v_bfe_u32 v27, v25, 16, 1
	v_add3_u32 v28, v25, v27, s51
	v_mov_b32_e32 v27, v197
	v_lshl_add_u64 v[20:21], v[20:21], 0, v[26:27]
	global_store_short_d16_hi v[20:21], v28, off
	v_add_f32_e32 v20, 0, v29
	v_add_f32_e32 v20, v20, v31
	v_add_f32_e32 v20, v20, v33
	v_add_f32_e32 v20, v20, v35
	s_waitcnt lgkmcnt(3)
	v_add_f32_e32 v20, v20, v32
	s_waitcnt lgkmcnt(2)
	v_add_f32_e32 v20, v20, v34
	s_waitcnt lgkmcnt(1)
	v_add_f32_e32 v20, v20, v39
	s_waitcnt lgkmcnt(0)
	v_add_f32_e32 v20, v20, v41
	s_waitcnt vmcnt(7)
	v_lshlrev_b32_e32 v26, 16, v59
	v_add_f32_e32 v20, v20, v26
	v_or_b32_e32 v21, v76, v53
	v_bfe_u32 v26, v20, 16, 1
	v_add3_u32 v34, v20, v26, s51
	v_lshlrev_b32_e32 v26, 1, v21
	v_lshl_add_u64 v[22:23], v[22:23], 0, v[26:27]
	ds_read2st64_b32 v[26:27], v57 offset0:32 offset1:40
	ds_read2st64_b32 v[28:29], v57 offset0:96 offset1:104
	ds_read2st64_b32 v[30:31], v57 offset0:160 offset1:168
	ds_read2st64_b32 v[32:33], v57 offset0:224 offset1:232
	global_store_short_d16_hi v[22:23], v34, off
	s_waitcnt lgkmcnt(3)
	v_add_f32_e32 v21, 0, v26
	s_waitcnt lgkmcnt(2)
	v_add_f32_e32 v21, v21, v28
	s_waitcnt lgkmcnt(1)
	v_add_f32_e32 v21, v21, v30
	s_waitcnt lgkmcnt(0)
	v_add_f32_e32 v21, v21, v32
	v_add_u32_e32 v22, 0x12000, v57
	v_add_u32_e32 v23, 0x16000, v57
	v_add_u32_e32 v26, 0x1a000, v57
	v_add_u32_e32 v28, 0x1e000, v57
	v_add_u32_e32 v30, 0x12800, v57
	v_add_u32_e32 v32, 0x16800, v57
	v_add_u32_e32 v34, 0x1a800, v57
	v_add_u32_e32 v35, 0x1e800, v57
	ds_read_b32 v22, v22
	ds_read_b32 v23, v23
	ds_read_b32 v26, v26
	ds_read_b32 v28, v28
	ds_read_b32 v30, v30
	ds_read_b32 v32, v32
	ds_read_b32 v34, v34
	ds_read_b32 v35, v35
	s_waitcnt lgkmcnt(7)
	v_add_f32_e32 v21, v21, v22
	s_waitcnt lgkmcnt(6)
	v_add_f32_e32 v21, v21, v23
	s_waitcnt lgkmcnt(5)
	v_add_f32_e32 v21, v21, v26
	s_waitcnt lgkmcnt(4)
	v_add_f32_e32 v21, v21, v28
	s_waitcnt vmcnt(7)
	v_lshlrev_b32_e32 v22, 16, v60
	v_add_f32_e32 v21, v21, v22
	v_bfe_u32 v22, v21, 16, 1
	v_add3_u32 v22, v21, v22, s51
	global_store_short_d16_hi v[16:17], v22, off
	v_add_f32_e32 v16, 0, v27
	v_add_f32_e32 v16, v16, v29
	v_add_f32_e32 v16, v16, v31
	v_add_f32_e32 v16, v16, v33
	s_waitcnt lgkmcnt(3)
	v_add_f32_e32 v16, v16, v30
	s_waitcnt lgkmcnt(2)
	v_add_f32_e32 v16, v16, v32
	s_waitcnt lgkmcnt(1)
	v_add_f32_e32 v16, v16, v34
	s_waitcnt lgkmcnt(0)
	v_add_f32_e32 v16, v16, v35
	s_waitcnt vmcnt(7)
; __device__ __forceinline__ unsigned f2bf(float f) { unsigned u = __builtin_bit_cast(unsigned, f); return (u + 0x7fffu + ((u >> 16) & 1u)) >> 16; }
; __device__ __forceinline__ int crow(int r, int hi) { return (r & 3) + 8 * (r >> 2) + 4 * hi; }
; __device__ __forceinline__ int crow(int r, int hi) { return (r & 3) + 8 * (r >> 2) + 4 * hi; }
; __device__ __forceinline__ int crow(int r, int hi) { return (r & 3) + 8 * (r >> 2) + 4 * hi; }
; template <int K>
; __device__ __forceinline__ void piece(LAS unsigned char* lds, int p, const bf16* A  , const bf16* Bt, bf16* xb  , float* rowsq  ) {
;     ...
;         for (int w = 0; w < 8; ++w) s += P[w * 4096 + e];
;         const int ln = e & 63, reg = (e >> 6) & 15, j = (e >> 10) & 1, i = e >> 11;
;         const int row = r0 + 32 * i + crow(reg, ln >> 5), col = c0 + 32 * j + (ln & 31);
;         const float v = bf2f(xin[q]) + s;
;         xb[(size_t)row * 1024 + col] = (bf16)f2bf(v); vv[q] = v; }
; #pragma unroll
;     for (int q = 0; q < 8; ++q) { if (q & 2) continue;
;         float sq = vv[q] * vv[q] + vv[q + 2] * vv[q + 2]; sq += __shfl_xor(sq, 1); sq += __shfl_xor(sq, 2); sq += __shfl_xor(sq, 4); sq += __shfl_xor(sq, 8); sq += __shfl_xor(sq, 16);
;         const int e = tid + 512 * q, ln = e & 63, reg = (e >> 6) & 15, i = e >> 11; const int row = r0 + 32 * i + crow(reg, ln >> 5);
;         if ((ln & 31) == 0) rowsq[(size_t)row * 16 + (p & 15)] = sq; }
	v_lshlrev_b32_e32 v22, 16, v36
	v_add_f32_e32 v16, v16, v22
	v_bfe_u32 v22, v16, 16, 1
	v_add3_u32 v32, v16, v22, s51
	ds_read2st64_b32 v[22:23], v57 offset0:48 offset1:56
	ds_read2st64_b32 v[26:27], v57 offset0:112 offset1:120
	ds_read2st64_b32 v[28:29], v57 offset0:176 offset1:184
	ds_read2st64_b32 v[30:31], v57 offset0:240 offset1:248
	v_or_b32_e32 v17, v76, v54
	v_lshlrev_b32_e32 v196, 1, v17
	s_waitcnt lgkmcnt(3)
	v_add_f32_e32 v17, 0, v22
	s_waitcnt lgkmcnt(2)
	v_add_f32_e32 v17, v17, v26
	v_lshl_add_u64 v[18:19], v[18:19], 0, v[196:197]
	s_waitcnt lgkmcnt(1)
	v_add_f32_e32 v17, v17, v28
	global_store_short_d16_hi v[18:19], v32, off
	s_waitcnt lgkmcnt(0)
	v_add_f32_e32 v17, v17, v30
	v_add_u32_e32 v18, 0x13000, v57
	v_add_u32_e32 v19, 0x17000, v57
	v_add_u32_e32 v22, 0x1b000, v57
	v_add_u32_e32 v26, 0x1f000, v57
	v_add_u32_e32 v28, 0x13800, v57
	v_add_u32_e32 v30, 0x17800, v57
	v_add_u32_e32 v32, 0x1b800, v57
	v_add_u32_e32 v33, 0x1f800, v57
	ds_read_b32 v18, v18
	ds_read_b32 v19, v19
	ds_read_b32 v22, v22
	ds_read_b32 v26, v26
	ds_read_b32 v28, v28
	ds_read_b32 v30, v30
	ds_read_b32 v32, v32
	ds_read_b32 v33, v33
	s_waitcnt lgkmcnt(7)
	v_add_f32_e32 v17, v17, v18
	s_waitcnt lgkmcnt(6)
	v_add_f32_e32 v17, v17, v19
	s_waitcnt lgkmcnt(5)
	v_add_f32_e32 v17, v17, v22
	s_waitcnt lgkmcnt(4)
	v_add_f32_e32 v17, v17, v26
	s_waitcnt vmcnt(7)
	v_lshlrev_b32_e32 v19, 16, v37
	v_or_b32_e32 v18, v76, v55
	v_add_f32_e32 v17, v17, v19
	v_bfe_u32 v19, v17, 16, 1
	v_lshlrev_b32_e32 v196, 1, v18
	v_add3_u32 v19, v17, v19, s51
	v_lshl_add_u64 v[14:15], v[14:15], 0, v[196:197]
	global_store_short_d16_hi v[14:15], v19, off
	v_add_f32_e32 v14, 0, v23
	v_add_f32_e32 v14, v14, v27
	v_and_b32_e32 v19, 64, v239
	v_add_f32_e32 v15, v14, v29
	v_mul_f32_e32 v18, v25, v25
	v_xor_b32_e32 v14, 1, v239
	v_add_u32_e32 v25, 64, v19
	v_cmp_lt_i32_e32 vcc, v14, v25
	v_fmac_f32_e32 v18, v40, v40
	v_add_f32_e32 v15, v15, v31
	v_cndmask_b32_e32 v14, v239, v14, vcc
	v_lshlrev_b32_e32 v14, 2, v14
	ds_bpermute_b32 v19, v14, v18
	s_waitcnt lgkmcnt(4)
	v_add_f32_e32 v15, v15, v28
	s_waitcnt lgkmcnt(3)
	v_add_f32_e32 v15, v15, v30
	s_waitcnt lgkmcnt(2)
	v_add_f32_e32 v22, v15, v32
	v_xor_b32_e32 v15, 2, v239
	v_cmp_lt_i32_e32 vcc, v15, v25
	s_waitcnt lgkmcnt(0)
	v_add_f32_e32 v18, v18, v19
	v_add_f32_e32 v19, v22, v33
	v_cndmask_b32_e32 v15, v239, v15, vcc
	v_lshlrev_b32_e32 v15, 2, v15
	ds_bpermute_b32 v23, v15, v18
	s_waitcnt vmcnt(7)
	v_lshlrev_b32_e32 v22, 16, v38
	v_add_f32_e32 v19, v19, v22
	v_bfe_u32 v22, v19, 16, 1
	v_add3_u32 v29, v19, v22, s51
	s_waitcnt lgkmcnt(0)
	v_add_f32_e32 v27, v18, v23
	v_xor_b32_e32 v18, 4, v239
	v_cmp_lt_i32_e32 vcc, v18, v25
	v_lshl_add_u64 v[22:23], s[0:1], 0, v[12:13]
	v_xor_b32_e32 v12, 8, v239
	v_cndmask_b32_e32 v18, v239, v18, vcc
	v_lshlrev_b32_e32 v18, 2, v18
	ds_bpermute_b32 v28, v18, v27
	v_cmp_lt_i32_e32 vcc, v12, v25
	v_or_b32_e32 v26, v76, v56
	v_lshlrev_b32_e32 v196, 1, v26
	v_cndmask_b32_e32 v12, v239, v12, vcc
	s_waitcnt lgkmcnt(0)
	v_add_f32_e32 v13, v27, v28
	v_lshlrev_b32_e32 v12, 2, v12
	ds_bpermute_b32 v26, v12, v13
	v_cmp_eq_u32_e32 vcc, 0, v3
	v_xor_b32_e32 v3, 16, v239
	v_cmp_lt_i32_e64 s[0:1], v3, v25
	v_lshl_add_u64 v[22:23], v[22:23], 0, v[196:197]
	s_waitcnt lgkmcnt(0)
	v_add_f32_e32 v13, v13, v26
	v_cndmask_b32_e64 v3, v239, v3, s[0:1]
	v_lshlrev_b32_e32 v3, 2, v3
	global_store_short_d16_hi v[22:23], v29, off
	ds_bpermute_b32 v22, v3, v13
	s_add_u32 s0, s8, s4
	s_addc_u32 s1, s9, 0
	s_add_u32 s0, s0, 0x24100000
	s_addc_u32 s1, s1, 0
	s_and_saveexec_b64 s[4:5], vcc
	s_cbranch_execz .LBB0_1037
	v_lshlrev_b64 v[6:7], 6, v[6:7]
	v_lshl_add_u64 v[6:7], s[0:1], 0, v[6:7]
	s_waitcnt lgkmcnt(0)
	v_add_f32_e32 v13, v13, v22
	global_store_dword v[6:7], v13, off
